# PLE gate epilogue: the -log2(e) factor of the sigmoid argument folded into the per-row rsqrt scale (one v_mul per row instead of one per element, same f32 math)
# speedup vs baseline: 1.0022x; 1.0022x over previous
.LBB0_1076:
	v_lshl_or_b32 v176, s36, 8, v221
	v_ashrrev_i32_e32 v177, 31, v176
	v_lshlrev_b64 v[124:125], 10, v[208:209]
	v_lshl_add_u64 v[124:125], v[124:125], 0, v[176:177]
	v_lshlrev_b64 v[124:125], 1, v[124:125]
	v_lshl_add_u64 v[126:127], s[14:15], 0, v[124:125]
	global_load_dwordx4 v[186:189], v[126:127], off
	v_lshl_add_u64 v[126:127], s[12:13], 0, v[124:125]
	global_load_dwordx4 v[210:213], v[126:127], off
	v_or_b32_e32 v182, 16, v208
	s_waitcnt vmcnt(0)
	v_fmamk_f32 v136, v232, 0x3a800000, v222
	v_ashrrev_i32_e32 v183, 31, v182
	v_mul_f32_e32 v137, 0x4b800000, v136
	v_lshlrev_b64 v[126:127], 10, v[182:183]
	v_cmp_gt_f32_e32 vcc, s65, v136
	v_lshl_add_u64 v[126:127], v[126:127], 0, v[176:177]
	v_or_b32_e32 v124, 0x100, v124
	v_cndmask_b32_e32 v136, v136, v137, vcc
	v_rsq_f32_e32 v218, v136
	v_lshlrev_b64 v[126:127], 1, v[126:127]
	v_lshl_add_u64 v[136:137], s[12:13], 0, v[124:125]
	v_lshl_add_u64 v[124:125], s[14:15], 0, v[124:125]
	v_lshl_add_u64 v[138:139], s[12:13], 0, v[126:127]
	v_lshl_add_u64 v[140:141], s[14:15], 0, v[126:127]
	global_load_dwordx4 v[214:217], v[136:137], off
	global_load_dwordx4 v[234:237], v[124:125], off
	global_load_dwordx4 v[168:171], v[138:139], off
	global_load_dwordx4 v[172:175], v[140:141], off
	v_or_b32_e32 v180, 32, v208
	v_or_b32_e32 v178, 48, v208
	v_ashrrev_i32_e32 v181, 31, v180
	v_ashrrev_i32_e32 v179, 31, v178
	v_lshlrev_b64 v[132:133], 10, v[180:181]
	v_lshlrev_b64 v[134:135], 10, v[178:179]
	v_lshl_add_u64 v[132:133], v[132:133], 0, v[176:177]
	v_lshl_add_u64 v[134:135], v[134:135], 0, v[176:177]
	v_lshlrev_b64 v[132:133], 1, v[132:133]
	v_lshlrev_b64 v[134:135], 1, v[134:135]
	v_or_b32_e32 v126, 0x100, v126
	v_lshl_add_u64 v[142:143], s[12:13], 0, v[132:133]
	v_lshl_add_u64 v[144:145], s[14:15], 0, v[132:133]
	v_or_b32_e32 v132, 0x100, v132
	v_lshl_add_u64 v[146:147], s[12:13], 0, v[134:135]
	v_lshl_add_u64 v[148:149], s[14:15], 0, v[134:135]
	v_lshl_add_u64 v[124:125], s[12:13], 0, v[126:127]
	global_load_dwordx4 v[152:155], v[142:143], off
	global_load_dwordx4 v[156:159], v[144:145], off
	v_lshl_add_u64 v[144:145], s[12:13], 0, v[132:133]
	v_lshl_add_u64 v[126:127], s[14:15], 0, v[126:127]
	v_lshl_add_u64 v[132:133], s[14:15], 0, v[132:133]
	global_load_dwordx4 v[136:139], v[146:147], off
	global_load_dwordx4 v[140:143], v[148:149], off
	global_load_dwordx4 v[160:163], v[124:125], off
	global_load_dwordx4 v[164:167], v[126:127], off
	s_nop 0
	global_load_dwordx4 v[144:147], v[144:145], off
	s_nop 0
	global_load_dwordx4 v[148:151], v[132:133], off
	v_mul_f32_e32 v124, 0x45800000, v218
	v_cndmask_b32_e32 v218, v218, v124, vcc
	v_mul_f32_e32 v218, 0xbfb8aa3b, v218
	v_or_b32_e32 v134, 0x100, v134
	v_mul_f32_e32 v124, v218, v128
	v_lshl_add_u64 v[190:191], s[12:13], 0, v[134:135]
	v_lshl_add_u64 v[134:135], s[14:15], 0, v[134:135]
	v_exp_f32_e32 v128, v124
	global_load_dwordx4 v[124:127], v[190:191], off
	s_nop 0
	global_load_dwordx4 v[132:135], v[134:135], off
	v_mul_f32_e32 v120, v218, v120
	v_exp_f32_e32 v120, v120
	v_mul_f32_e32 v121, v218, v121
	v_exp_f32_e32 v121, v121
	v_add_f32_e32 v120, 1.0, v120
	v_rcp_f32_e32 v120, v120
	v_mul_f32_e32 v122, v218, v122
	v_exp_f32_e32 v122, v122
	v_mul_f32_e32 v123, v218, v123
	v_exp_f32_e32 v123, v123
	v_mul_f32_e32 v112, v218, v112
	v_exp_f32_e32 v112, v112
	v_mul_f32_e32 v129, v218, v129
	v_add_f32_e32 v123, 1.0, v123
	v_rcp_f32_e32 v123, v123
	v_mul_f32_e32 v113, v218, v113
	v_exp_f32_e32 v129, v129
	v_add_f32_e32 v112, 1.0, v112
	v_rcp_f32_e32 v112, v112
	v_exp_f32_e32 v113, v113
	v_add_f32_e32 v129, 1.0, v129
	v_add_f32_e32 v128, 1.0, v128
	v_lshlrev_b32_e32 v219, 16, v188
	v_and_b32_e32 v188, 0xffff0000, v188
	v_lshlrev_b32_e32 v240, 16, v212
	v_fmac_f32_e32 v240, v120, v219
	v_add_f32_e32 v120, 1.0, v121
	v_mul_f32_e32 v121, v218, v130
	v_rcp_f32_e32 v120, v120
	v_exp_f32_e32 v121, v121
	v_and_b32_e32 v212, 0xffff0000, v212
	v_lshlrev_b32_e32 v233, 16, v189
	v_fmac_f32_e32 v212, v120, v188
	v_add_f32_e32 v120, 1.0, v121
	v_add_f32_e32 v121, 1.0, v122
	v_mul_f32_e32 v122, v218, v131
	v_exp_f32_e32 v122, v122
	v_rcp_f32_e32 v121, v121
	v_and_b32_e32 v189, 0xffff0000, v189
	v_lshlrev_b32_e32 v241, 16, v213
	v_add_f32_e32 v122, 1.0, v122
	v_rcp_f32_e32 v122, v122
	v_and_b32_e32 v213, 0xffff0000, v213
	v_lshlrev_b32_e32 v191, 16, v187
	v_and_b32_e32 v187, 0xffff0000, v187
	v_lshlrev_b32_e32 v239, 16, v211
	v_and_b32_e32 v211, 0xffff0000, v211
	v_fmac_f32_e32 v213, v123, v189
	v_fmac_f32_e32 v241, v121, v233
	v_fmac_f32_e32 v211, v122, v187
	v_cvt_pk_bf16_f32 v131, v241, v213
	v_mul_f32_e32 v122, v213, v213
	s_waitcnt vmcnt(12)
	v_lshlrev_b32_e32 v187, 16, v236
	v_lshlrev_b32_e32 v213, 16, v216
	v_rcp_f32_e32 v129, v129
	v_fmac_f32_e32 v213, v112, v187
	v_add_f32_e32 v112, 1.0, v113
	v_mul_f32_e32 v113, v218, v118
	v_mul_f32_e32 v114, v218, v114
	v_rcp_f32_e32 v128, v128
	v_rcp_f32_e32 v120, v120
	v_rcp_f32_e32 v112, v112
	v_exp_f32_e32 v113, v113
	v_exp_f32_e32 v114, v114
	v_lshlrev_b32_e32 v190, 16, v186
	v_and_b32_e32 v186, 0xffff0000, v186
	v_lshlrev_b32_e32 v238, 16, v210
	v_and_b32_e32 v210, 0xffff0000, v210
	v_fmac_f32_e32 v210, v129, v186
	v_fmac_f32_e32 v238, v128, v190
	v_fmac_f32_e32 v239, v120, v191
	v_cvt_pk_bf16_f32 v128, v238, v210
	v_mul_f32_e32 v120, v210, v210
	v_and_b32_e32 v188, 0xffff0000, v236
	v_lshlrev_b32_e32 v191, 16, v214
	v_and_b32_e32 v210, 0xffff0000, v214
	v_and_b32_e32 v214, 0xffff0000, v216
	v_mul_f32_e32 v117, v218, v117
	v_fmac_f32_e32 v214, v112, v188
	v_add_f32_e32 v112, 1.0, v113
	v_add_f32_e32 v113, 1.0, v114
	v_mul_f32_e32 v114, v218, v119
	v_mul_f32_e32 v116, v218, v116
	v_exp_f32_e32 v117, v117
	v_exp_f32_e32 v114, v114
	v_mul_f32_e32 v115, v218, v115
	v_exp_f32_e32 v116, v116
	v_exp_f32_e32 v115, v115
	v_mul_f32_e32 v121, v211, v211
	v_add_f32_e32 v117, 1.0, v117
	v_add_f32_e32 v114, 1.0, v114
	v_fmac_f32_e32 v120, v238, v238
	v_fmac_f32_e32 v121, v239, v239
	v_add_f32_e32 v116, 1.0, v116
	v_rcp_f32_e32 v117, v117
	v_rcp_f32_e32 v114, v114
	v_add_f32_e32 v120, v120, v121
	v_mul_f32_e32 v121, v212, v212
	v_rcp_f32_e32 v116, v116
	v_rcp_f32_e32 v112, v112
	v_rcp_f32_e32 v113, v113
	v_add_f32_e32 v115, 1.0, v115
	v_fmac_f32_e32 v121, v240, v240
	v_fmac_f32_e32 v122, v241, v241
	v_rcp_f32_e32 v115, v115
	v_cvt_pk_bf16_f32 v130, v240, v212
	v_add_f32_e32 v121, v121, v122
	v_and_b32_e32 v122, 0xffff0000, v234
	v_and_b32_e32 v186, 0xffff0000, v235
	v_and_b32_e32 v212, 0xffff0000, v215
	v_cvt_pk_bf16_f32 v129, v239, v211
	v_add_f32_e32 v120, v120, v121
	v_lshlrev_b32_e32 v121, 16, v234
	v_lshlrev_b32_e32 v123, 16, v235
	v_lshlrev_b32_e32 v189, 16, v237
	v_lshlrev_b32_e32 v211, 16, v215
	v_lshlrev_b32_e32 v215, 16, v217
	v_fmac_f32_e32 v210, v117, v122
	v_fmac_f32_e32 v212, v114, v186
	v_and_b32_e32 v190, 0xffff0000, v237
	v_and_b32_e32 v216, 0xffff0000, v217
	v_fmac_f32_e32 v191, v116, v121
	v_fmac_f32_e32 v211, v112, v123
	v_fmac_f32_e32 v215, v113, v189
	v_mul_f32_e32 v112, v210, v210
	v_mul_f32_e32 v113, v212, v212
	v_fmac_f32_e32 v216, v115, v190
	v_fmac_f32_e32 v112, v191, v191
	v_fmac_f32_e32 v113, v211, v211
	v_add_f32_e32 v112, v112, v113
	v_mul_f32_e32 v113, v214, v214
	v_mul_f32_e32 v114, v216, v216
	v_fmac_f32_e32 v113, v213, v213
	v_fmac_f32_e32 v114, v215, v215
	v_add_f32_e32 v113, v113, v114
	v_add_f32_e32 v112, v112, v113
	v_and_b32_e32 v113, 64, v223
	v_add_f32_e32 v115, v120, v112
	v_xor_b32_e32 v112, 16, v223
	v_add_u32_e32 v116, 64, v113
	v_cmp_lt_i32_e32 vcc, v112, v116
	v_lshlrev_b64 v[184:185], 11, v[208:209]
	v_cvt_pk_bf16_f32 v114, v191, v210
	s_nop 0
	v_cndmask_b32_e32 v112, v223, v112, vcc
	v_lshlrev_b32_e32 v122, 2, v112
	ds_bpermute_b32 v117, v122, v115
	v_lshl_add_u64 v[112:113], s[70:71], 0, v[184:185]
	v_lshl_add_u64 v[118:119], v[176:177], 1, v[112:113]
	v_xor_b32_e32 v113, 32, v223
	v_cmp_lt_i32_e32 vcc, v113, v116
	s_waitcnt lgkmcnt(0)
	v_add_f32_e32 v112, v115, v117
	global_store_dwordx4 v[118:119], v[128:131], off
	v_cndmask_b32_e32 v113, v223, v113, vcc
	v_lshlrev_b32_e32 v123, 2, v113
	ds_bpermute_b32 v113, v123, v112
	v_cvt_pk_bf16_f32 v115, v211, v212
	v_cvt_pk_bf16_f32 v116, v213, v214
	v_cvt_pk_bf16_f32 v117, v215, v216
	global_store_dwordx4 v[118:119], v[114:117], off offset:256
	s_and_saveexec_b64 s[36:37], s[4:5]
	s_cbranch_execz .LBB0_1078
	v_lshl_add_u64 v[114:115], v[208:209], 2, s[16:17]
	s_waitcnt lgkmcnt(0)
	v_add_f32_e32 v112, v112, v113
	global_atomic_add_f32 v[114:115], v112, off
.LBB0_1078:
	s_or_b64 exec, exec, s[36:37]
	v_fmamk_f32 v112, v231, 0x3a800000, v222
	s_waitcnt lgkmcnt(0)
	v_mul_f32_e32 v113, 0x4b800000, v112
	v_cmp_gt_f32_e32 vcc, s65, v112
	s_waitcnt vmcnt(12)
	v_lshlrev_b32_e32 v119, 16, v174
	v_lshlrev_b32_e32 v129, 16, v168
	v_cndmask_b32_e32 v112, v112, v113, vcc
	v_rsq_f32_e32 v114, v112
	v_and_b32_e32 v130, 0xffff0000, v168
	v_lshlrev_b32_e32 v131, 16, v169
	v_and_b32_e32 v168, 0xffff0000, v169
	v_mul_f32_e32 v116, 0x45800000, v114
	v_cndmask_b32_e32 v114, v114, v116, vcc
	v_mul_f32_e32 v114, 0xbfb8aa3b, v114
	v_mul_f32_e32 v104, v114, v104
	v_exp_f32_e32 v104, v104
	v_mul_f32_e32 v105, v114, v105
	v_exp_f32_e32 v105, v105
	v_add_f32_e32 v104, 1.0, v104
	v_rcp_f32_e32 v104, v104
	v_lshlrev_b32_e32 v169, 16, v170
	v_mul_f32_e32 v106, v114, v106
	v_mul_f32_e32 v109, v114, v109
	v_fmac_f32_e32 v169, v104, v119
	v_add_f32_e32 v104, 1.0, v105
	v_mul_f32_e32 v105, v114, v110
	v_mul_f32_e32 v108, v114, v108
	v_rcp_f32_e32 v104, v104
	v_exp_f32_e32 v105, v105
	v_exp_f32_e32 v106, v106
	v_exp_f32_e32 v109, v109
	v_mul_f32_e32 v96, v114, v96
	v_exp_f32_e32 v108, v108
	v_and_b32_e32 v120, 0xffff0000, v174
	v_and_b32_e32 v170, 0xffff0000, v170
	v_exp_f32_e32 v96, v96
	v_fmac_f32_e32 v170, v104, v120
	v_add_f32_e32 v104, 1.0, v105
	v_add_f32_e32 v105, 1.0, v106
	v_mul_f32_e32 v106, v114, v111
	v_add_f32_e32 v109, 1.0, v109
	v_add_f32_e32 v108, 1.0, v108
	v_rcp_f32_e32 v109, v109
	v_exp_f32_e32 v106, v106
	v_mul_f32_e32 v97, v114, v97
	v_rcp_f32_e32 v108, v108
	v_rcp_f32_e32 v104, v104
	v_add_f32_e32 v96, 1.0, v96
	v_rcp_f32_e32 v96, v96
	v_exp_f32_e32 v97, v97
	v_and_b32_e32 v116, 0xffff0000, v172
	v_lshlrev_b32_e32 v115, 16, v172
	v_lshlrev_b32_e32 v117, 16, v173
	v_fmac_f32_e32 v130, v109, v116
	v_add_f32_e32 v106, 1.0, v106
	v_fmac_f32_e32 v129, v108, v115
	v_rcp_f32_e32 v106, v106
	v_fmac_f32_e32 v131, v104, v117
	v_cvt_pk_bf16_f32 v104, v129, v130
	v_mul_f32_e32 v108, v130, v130
	s_waitcnt vmcnt(6)
	v_lshlrev_b32_e32 v116, 16, v166
	v_lshlrev_b32_e32 v130, 16, v162
	v_fmac_f32_e32 v130, v96, v116
	v_add_f32_e32 v96, 1.0, v97
	v_mul_f32_e32 v97, v114, v102
	v_mul_f32_e32 v98, v114, v98
	v_rcp_f32_e32 v105, v105
	v_and_b32_e32 v118, 0xffff0000, v173
	v_mul_f32_e32 v107, v114, v107
	v_rcp_f32_e32 v96, v96
	v_exp_f32_e32 v97, v97
	v_exp_f32_e32 v98, v98
	v_fmac_f32_e32 v168, v106, v118
	v_lshlrev_b32_e32 v121, 16, v175
	v_lshlrev_b32_e32 v172, 16, v171
	v_exp_f32_e32 v107, v107
	v_mul_f32_e32 v109, v168, v168
	v_fmac_f32_e32 v172, v105, v121
	v_cvt_pk_bf16_f32 v105, v131, v168
	v_fmac_f32_e32 v109, v131, v131
	v_and_b32_e32 v117, 0xffff0000, v166
	v_and_b32_e32 v131, 0xffff0000, v162
	v_mul_f32_e32 v101, v114, v101
	v_fmac_f32_e32 v131, v96, v117
	v_add_f32_e32 v96, 1.0, v97
	v_add_f32_e32 v97, 1.0, v98
	v_mul_f32_e32 v98, v114, v103
	v_mul_f32_e32 v100, v114, v100
	v_add_f32_e32 v107, 1.0, v107
	v_exp_f32_e32 v101, v101
	v_exp_f32_e32 v98, v98
	v_mul_f32_e32 v99, v114, v99
	v_rcp_f32_e32 v107, v107
	v_exp_f32_e32 v100, v100
	v_exp_f32_e32 v99, v99
	v_and_b32_e32 v128, 0xffff0000, v175
	v_and_b32_e32 v171, 0xffff0000, v171
	v_add_f32_e32 v101, 1.0, v101
	v_add_f32_e32 v98, 1.0, v98
	v_fmac_f32_e32 v171, v107, v128
	v_fmac_f32_e32 v108, v129, v129
	v_add_f32_e32 v100, 1.0, v100
	v_rcp_f32_e32 v101, v101
	v_rcp_f32_e32 v98, v98
	v_add_f32_e32 v108, v108, v109
	v_mul_f32_e32 v109, v170, v170
	v_mul_f32_e32 v110, v171, v171
	v_rcp_f32_e32 v100, v100
	v_rcp_f32_e32 v96, v96
	v_rcp_f32_e32 v97, v97
	v_add_f32_e32 v99, 1.0, v99
	v_fmac_f32_e32 v109, v169, v169
	v_fmac_f32_e32 v110, v172, v172
	v_rcp_f32_e32 v99, v99
	v_add_f32_e32 v109, v109, v110
	v_and_b32_e32 v110, 0xffff0000, v164
	v_and_b32_e32 v115, 0xffff0000, v165
	v_and_b32_e32 v121, 0xffff0000, v160
	v_and_b32_e32 v129, 0xffff0000, v161
	v_add_f32_e32 v108, v108, v109
	v_lshlrev_b32_e32 v109, 16, v164
	v_lshlrev_b32_e32 v111, 16, v165
	v_lshlrev_b32_e32 v118, 16, v167
	v_lshlrev_b32_e32 v120, 16, v160
	v_lshlrev_b32_e32 v128, 16, v161
	v_lshlrev_b32_e32 v160, 16, v163
	v_fmac_f32_e32 v121, v101, v110
	v_fmac_f32_e32 v129, v98, v115
	v_and_b32_e32 v119, 0xffff0000, v167
	v_and_b32_e32 v161, 0xffff0000, v163
	v_fmac_f32_e32 v120, v100, v109
	v_fmac_f32_e32 v128, v96, v111
	v_fmac_f32_e32 v160, v97, v118
	v_mul_f32_e32 v96, v121, v121
	v_mul_f32_e32 v97, v129, v129
	v_fmac_f32_e32 v161, v99, v119
	v_fmac_f32_e32 v96, v120, v120
	v_fmac_f32_e32 v97, v128, v128
	v_add_f32_e32 v96, v96, v97
	v_mul_f32_e32 v97, v131, v131
	v_mul_f32_e32 v98, v161, v161
	v_fmac_f32_e32 v97, v130, v130
	v_fmac_f32_e32 v98, v160, v160
	v_add_f32_e32 v97, v97, v98
	v_add_f32_e32 v96, v96, v97
	v_add_f32_e32 v99, v108, v96
	ds_bpermute_b32 v100, v122, v99
	v_lshlrev_b64 v[112:113], 11, v[182:183]
	v_lshl_add_u64 v[96:97], s[70:71], 0, v[112:113]
	v_lshl_add_u64 v[102:103], v[176:177], 1, v[96:97]
	v_cvt_pk_bf16_f32 v106, v169, v170
	s_waitcnt lgkmcnt(0)
	v_add_f32_e32 v96, v99, v100
	ds_bpermute_b32 v97, v123, v96
	v_cvt_pk_bf16_f32 v107, v172, v171
	global_store_dwordx4 v[102:103], v[104:107], off
	v_cvt_pk_bf16_f32 v98, v120, v121
	v_cvt_pk_bf16_f32 v99, v128, v129
	v_cvt_pk_bf16_f32 v100, v130, v131
	v_cvt_pk_bf16_f32 v101, v160, v161
	global_store_dwordx4 v[102:103], v[98:101], off offset:256
	s_and_saveexec_b64 s[36:37], s[4:5]
	s_cbranch_execz .LBB0_1080
	v_lshl_add_u64 v[98:99], v[182:183], 2, s[16:17]
	s_waitcnt lgkmcnt(0)
	v_add_f32_e32 v96, v96, v97
	global_atomic_add_f32 v[98:99], v96, off
.LBB0_1080:
	s_or_b64 exec, exec, s[36:37]
	v_fmamk_f32 v96, v230, 0x3a800000, v222
	s_waitcnt lgkmcnt(0)
	v_mul_f32_e32 v97, 0x4b800000, v96
	v_cmp_gt_f32_e32 vcc, s65, v96
	v_lshlrev_b32_e32 v103, 16, v158
	v_lshlrev_b32_e32 v111, 16, v154
	v_cndmask_b32_e32 v96, v96, v97, vcc
	v_rsq_f32_e32 v98, v96
	v_and_b32_e32 v104, 0xffff0000, v158
	v_and_b32_e32 v112, 0xffff0000, v154
	v_and_b32_e32 v108, 0xffff0000, v152
	v_mul_f32_e32 v100, 0x45800000, v98
	v_cndmask_b32_e32 v98, v98, v100, vcc
	v_mul_f32_e32 v98, 0xbfb8aa3b, v98
	v_mul_f32_e32 v88, v98, v88
	v_exp_f32_e32 v88, v88
	v_mul_f32_e32 v89, v98, v89
	v_exp_f32_e32 v89, v89
	v_add_f32_e32 v88, 1.0, v88
	v_rcp_f32_e32 v88, v88
	v_mul_f32_e32 v90, v98, v90
	v_mul_f32_e32 v93, v98, v93
	v_fmac_f32_e32 v111, v88, v103
	v_add_f32_e32 v88, 1.0, v89
	v_mul_f32_e32 v89, v98, v94
	v_mul_f32_e32 v92, v98, v92
	v_rcp_f32_e32 v88, v88
	v_exp_f32_e32 v89, v89
	v_exp_f32_e32 v90, v90
	v_exp_f32_e32 v93, v93
	v_mul_f32_e32 v80, v98, v80
	v_exp_f32_e32 v92, v92
	v_exp_f32_e32 v80, v80
	v_fmac_f32_e32 v112, v88, v104
	v_add_f32_e32 v88, 1.0, v89
	v_add_f32_e32 v89, 1.0, v90
	v_mul_f32_e32 v90, v98, v95
	v_add_f32_e32 v93, 1.0, v93
	v_add_f32_e32 v92, 1.0, v92
	v_rcp_f32_e32 v93, v93
	v_exp_f32_e32 v90, v90
	v_mul_f32_e32 v81, v98, v81
	v_rcp_f32_e32 v92, v92
	v_rcp_f32_e32 v88, v88
	v_add_f32_e32 v80, 1.0, v80
	v_rcp_f32_e32 v80, v80
	v_exp_f32_e32 v81, v81
	v_and_b32_e32 v100, 0xffff0000, v156
	v_lshlrev_b32_e32 v99, 16, v156
	v_lshlrev_b32_e32 v101, 16, v157
	v_lshlrev_b32_e32 v107, 16, v152
	v_lshlrev_b32_e32 v109, 16, v153
	v_fmac_f32_e32 v108, v93, v100
	v_add_f32_e32 v90, 1.0, v90
	v_fmac_f32_e32 v107, v92, v99
	v_rcp_f32_e32 v90, v90
	v_fmac_f32_e32 v109, v88, v101
	v_cvt_pk_bf16_f32 v88, v107, v108
	v_mul_f32_e32 v92, v108, v108
	s_waitcnt vmcnt(6)
	v_lshlrev_b32_e32 v100, 16, v150
	v_lshlrev_b32_e32 v108, 16, v146
	v_fmac_f32_e32 v108, v80, v100
	v_add_f32_e32 v80, 1.0, v81
	v_mul_f32_e32 v81, v98, v86
	v_mul_f32_e32 v82, v98, v82
	v_rcp_f32_e32 v89, v89
	v_and_b32_e32 v102, 0xffff0000, v157
	v_and_b32_e32 v110, 0xffff0000, v153
	v_mul_f32_e32 v91, v98, v91
	v_rcp_f32_e32 v80, v80
	v_exp_f32_e32 v81, v81
	v_exp_f32_e32 v82, v82
	v_fmac_f32_e32 v110, v90, v102
	v_lshlrev_b32_e32 v105, 16, v159
	v_lshlrev_b32_e32 v113, 16, v155
	v_exp_f32_e32 v91, v91
	v_mul_f32_e32 v93, v110, v110
	v_fmac_f32_e32 v113, v89, v105
	v_cvt_pk_bf16_f32 v89, v109, v110
	v_fmac_f32_e32 v93, v109, v109
	v_and_b32_e32 v101, 0xffff0000, v150
	v_and_b32_e32 v109, 0xffff0000, v146
	v_mul_f32_e32 v85, v98, v85
	v_fmac_f32_e32 v109, v80, v101
	v_add_f32_e32 v80, 1.0, v81
	v_add_f32_e32 v81, 1.0, v82
	v_mul_f32_e32 v82, v98, v87
	v_mul_f32_e32 v84, v98, v84
	v_add_f32_e32 v91, 1.0, v91
	v_exp_f32_e32 v85, v85
	v_exp_f32_e32 v82, v82
	v_mul_f32_e32 v83, v98, v83
	v_rcp_f32_e32 v91, v91
	v_exp_f32_e32 v84, v84
	v_exp_f32_e32 v83, v83
	v_and_b32_e32 v106, 0xffff0000, v159
	v_and_b32_e32 v114, 0xffff0000, v155
	v_add_f32_e32 v85, 1.0, v85
	v_add_f32_e32 v82, 1.0, v82
	v_fmac_f32_e32 v114, v91, v106
	v_fmac_f32_e32 v92, v107, v107
	v_add_f32_e32 v84, 1.0, v84
	v_rcp_f32_e32 v85, v85
	v_rcp_f32_e32 v82, v82
	v_add_f32_e32 v92, v92, v93
	v_mul_f32_e32 v93, v112, v112
	v_mul_f32_e32 v94, v114, v114
	v_rcp_f32_e32 v84, v84
	v_rcp_f32_e32 v80, v80
	v_rcp_f32_e32 v81, v81
	v_add_f32_e32 v83, 1.0, v83
	v_fmac_f32_e32 v93, v111, v111
	v_fmac_f32_e32 v94, v113, v113
	v_rcp_f32_e32 v83, v83
	v_add_f32_e32 v93, v93, v94
	v_and_b32_e32 v94, 0xffff0000, v148
	v_and_b32_e32 v99, 0xffff0000, v149
	v_and_b32_e32 v105, 0xffff0000, v144
	v_and_b32_e32 v107, 0xffff0000, v145
	v_add_f32_e32 v92, v92, v93
	v_lshlrev_b32_e32 v93, 16, v148
	v_lshlrev_b32_e32 v95, 16, v149
	v_lshlrev_b32_e32 v102, 16, v151
	v_lshlrev_b32_e32 v104, 16, v144
	v_lshlrev_b32_e32 v106, 16, v145
	v_lshlrev_b32_e32 v110, 16, v147
	v_fmac_f32_e32 v105, v85, v94
	v_fmac_f32_e32 v107, v82, v99
	v_cvt_pk_bf16_f32 v90, v111, v112
	v_and_b32_e32 v103, 0xffff0000, v151
	v_and_b32_e32 v111, 0xffff0000, v147
	v_fmac_f32_e32 v104, v84, v93
	v_fmac_f32_e32 v106, v80, v95
	v_fmac_f32_e32 v110, v81, v102
	v_mul_f32_e32 v80, v105, v105
	v_mul_f32_e32 v81, v107, v107
	v_fmac_f32_e32 v111, v83, v103
	v_fmac_f32_e32 v80, v104, v104
	v_fmac_f32_e32 v81, v106, v106
	v_add_f32_e32 v80, v80, v81
	v_mul_f32_e32 v81, v109, v109
	v_mul_f32_e32 v82, v111, v111
	v_fmac_f32_e32 v81, v108, v108
	v_fmac_f32_e32 v82, v110, v110
	v_add_f32_e32 v81, v81, v82
	v_add_f32_e32 v80, v80, v81
	v_add_f32_e32 v83, v92, v80
	ds_bpermute_b32 v84, v122, v83
	v_lshlrev_b64 v[96:97], 11, v[180:181]
	v_lshl_add_u64 v[80:81], s[70:71], 0, v[96:97]
	v_lshl_add_u64 v[86:87], v[176:177], 1, v[80:81]
	v_cvt_pk_bf16_f32 v91, v113, v114
	s_waitcnt lgkmcnt(0)
	v_add_f32_e32 v80, v83, v84
	ds_bpermute_b32 v81, v123, v80
	global_store_dwordx4 v[86:87], v[88:91], off
	v_cvt_pk_bf16_f32 v82, v104, v105
	v_cvt_pk_bf16_f32 v83, v106, v107
	v_cvt_pk_bf16_f32 v84, v108, v109
	v_cvt_pk_bf16_f32 v85, v110, v111
	global_store_dwordx4 v[86:87], v[82:85], off offset:256
	s_and_saveexec_b64 s[36:37], s[4:5]
	s_cbranch_execz .LBB0_1082
	v_lshl_add_u64 v[82:83], v[180:181], 2, s[16:17]
	s_waitcnt lgkmcnt(0)
	v_add_f32_e32 v80, v80, v81
	global_atomic_add_f32 v[82:83], v80, off
.LBB0_1082:
	s_or_b64 exec, exec, s[36:37]
	v_fmamk_f32 v80, v229, 0x3a800000, v222
	s_waitcnt lgkmcnt(0)
	v_mul_f32_e32 v81, 0x4b800000, v80
	v_cmp_gt_f32_e32 vcc, s65, v80
	v_lshlrev_b32_e32 v87, 16, v142
	v_lshlrev_b32_e32 v95, 16, v138
	v_cndmask_b32_e32 v80, v80, v81, vcc
	v_rsq_f32_e32 v82, v80
	v_and_b32_e32 v88, 0xffff0000, v142
	v_and_b32_e32 v96, 0xffff0000, v138
	v_and_b32_e32 v92, 0xffff0000, v136
	v_mul_f32_e32 v84, 0x45800000, v82
	v_cndmask_b32_e32 v82, v82, v84, vcc
	v_mul_f32_e32 v82, 0xbfb8aa3b, v82
	v_mul_f32_e32 v72, v82, v72
	v_exp_f32_e32 v72, v72
	v_mul_f32_e32 v73, v82, v73
	v_exp_f32_e32 v73, v73
	v_add_f32_e32 v72, 1.0, v72
	v_rcp_f32_e32 v72, v72
	v_mul_f32_e32 v74, v82, v74
	v_mul_f32_e32 v77, v82, v77
	v_fmac_f32_e32 v95, v72, v87
	v_add_f32_e32 v72, 1.0, v73
	v_mul_f32_e32 v73, v82, v78
	v_mul_f32_e32 v76, v82, v76
	v_rcp_f32_e32 v72, v72
	v_exp_f32_e32 v73, v73
	v_exp_f32_e32 v74, v74
	v_exp_f32_e32 v77, v77
	v_mul_f32_e32 v64, v82, v64
	v_exp_f32_e32 v76, v76
	v_exp_f32_e32 v64, v64
	v_fmac_f32_e32 v96, v72, v88
	v_add_f32_e32 v72, 1.0, v73
	v_add_f32_e32 v73, 1.0, v74
	v_mul_f32_e32 v74, v82, v79
	v_add_f32_e32 v77, 1.0, v77
	v_add_f32_e32 v76, 1.0, v76
	v_rcp_f32_e32 v77, v77
	v_exp_f32_e32 v74, v74
	v_mul_f32_e32 v65, v82, v65
	v_rcp_f32_e32 v76, v76
	v_rcp_f32_e32 v72, v72
	v_add_f32_e32 v64, 1.0, v64
	v_rcp_f32_e32 v64, v64
	v_exp_f32_e32 v65, v65
	v_and_b32_e32 v84, 0xffff0000, v140
	v_lshlrev_b32_e32 v83, 16, v140
	v_lshlrev_b32_e32 v85, 16, v141
	v_lshlrev_b32_e32 v91, 16, v136
	v_lshlrev_b32_e32 v93, 16, v137
	v_fmac_f32_e32 v92, v77, v84
	v_add_f32_e32 v74, 1.0, v74
	v_fmac_f32_e32 v91, v76, v83
	v_rcp_f32_e32 v74, v74
	v_fmac_f32_e32 v93, v72, v85
	v_cvt_pk_bf16_f32 v72, v91, v92
	v_mul_f32_e32 v76, v92, v92
	s_waitcnt vmcnt(6)
	v_lshlrev_b32_e32 v84, 16, v134
	v_lshlrev_b32_e32 v92, 16, v126
	v_fmac_f32_e32 v92, v64, v84
	v_add_f32_e32 v64, 1.0, v65
	v_mul_f32_e32 v65, v82, v70
	v_mul_f32_e32 v66, v82, v66
	v_rcp_f32_e32 v73, v73
	v_and_b32_e32 v86, 0xffff0000, v141
	v_and_b32_e32 v94, 0xffff0000, v137
	v_mul_f32_e32 v75, v82, v75
	v_rcp_f32_e32 v64, v64
	v_exp_f32_e32 v65, v65
	v_exp_f32_e32 v66, v66
	v_fmac_f32_e32 v94, v74, v86
	v_lshlrev_b32_e32 v89, 16, v143
	v_lshlrev_b32_e32 v97, 16, v139
	v_exp_f32_e32 v75, v75
	v_mul_f32_e32 v77, v94, v94
	v_fmac_f32_e32 v97, v73, v89
	v_cvt_pk_bf16_f32 v73, v93, v94
	v_fmac_f32_e32 v77, v93, v93
	v_and_b32_e32 v85, 0xffff0000, v134
	v_and_b32_e32 v93, 0xffff0000, v126
	v_mul_f32_e32 v69, v82, v69
	v_fmac_f32_e32 v93, v64, v85
	v_add_f32_e32 v64, 1.0, v65
	v_add_f32_e32 v65, 1.0, v66
	v_mul_f32_e32 v66, v82, v71
	v_mul_f32_e32 v68, v82, v68
	v_add_f32_e32 v75, 1.0, v75
	v_exp_f32_e32 v69, v69
	v_exp_f32_e32 v66, v66
	v_mul_f32_e32 v67, v82, v67
	v_rcp_f32_e32 v75, v75
	v_exp_f32_e32 v68, v68
	v_exp_f32_e32 v67, v67
	v_and_b32_e32 v90, 0xffff0000, v143
	v_and_b32_e32 v98, 0xffff0000, v139
	v_add_f32_e32 v69, 1.0, v69
	v_add_f32_e32 v66, 1.0, v66
	v_fmac_f32_e32 v98, v75, v90
	v_fmac_f32_e32 v76, v91, v91
	v_add_f32_e32 v68, 1.0, v68
	v_rcp_f32_e32 v69, v69
	v_rcp_f32_e32 v66, v66
	v_add_f32_e32 v76, v76, v77
	v_mul_f32_e32 v77, v96, v96
	v_mul_f32_e32 v78, v98, v98
	v_rcp_f32_e32 v68, v68
	v_rcp_f32_e32 v64, v64
	v_rcp_f32_e32 v65, v65
	v_add_f32_e32 v67, 1.0, v67
	v_fmac_f32_e32 v77, v95, v95
	v_fmac_f32_e32 v78, v97, v97
	v_rcp_f32_e32 v67, v67
	v_add_f32_e32 v77, v77, v78
	v_and_b32_e32 v78, 0xffff0000, v132
	v_and_b32_e32 v83, 0xffff0000, v133
	v_and_b32_e32 v89, 0xffff0000, v124
	v_and_b32_e32 v91, 0xffff0000, v125
	v_add_f32_e32 v76, v76, v77
	v_lshlrev_b32_e32 v77, 16, v132
	v_lshlrev_b32_e32 v79, 16, v133
	v_lshlrev_b32_e32 v86, 16, v135
	v_lshlrev_b32_e32 v88, 16, v124
	v_lshlrev_b32_e32 v90, 16, v125
	v_lshlrev_b32_e32 v94, 16, v127
	v_fmac_f32_e32 v89, v69, v78
	v_fmac_f32_e32 v91, v66, v83
	v_cvt_pk_bf16_f32 v74, v95, v96
	v_and_b32_e32 v87, 0xffff0000, v135
	v_and_b32_e32 v95, 0xffff0000, v127
	v_fmac_f32_e32 v88, v68, v77
	v_fmac_f32_e32 v90, v64, v79
	v_fmac_f32_e32 v94, v65, v86
	v_mul_f32_e32 v64, v89, v89
	v_mul_f32_e32 v65, v91, v91
	v_fmac_f32_e32 v95, v67, v87
	v_fmac_f32_e32 v64, v88, v88
	v_fmac_f32_e32 v65, v90, v90
	v_add_f32_e32 v64, v64, v65
	v_mul_f32_e32 v65, v93, v93
	v_mul_f32_e32 v66, v95, v95
	v_fmac_f32_e32 v65, v92, v92
	v_fmac_f32_e32 v66, v94, v94
	v_add_f32_e32 v65, v65, v66
	v_add_f32_e32 v64, v64, v65
	v_add_f32_e32 v67, v76, v64
	ds_bpermute_b32 v68, v122, v67
	v_lshlrev_b64 v[80:81], 11, v[178:179]
	v_lshl_add_u64 v[64:65], s[70:71], 0, v[80:81]
	v_lshl_add_u64 v[70:71], v[176:177], 1, v[64:65]
	v_cvt_pk_bf16_f32 v75, v97, v98
	s_waitcnt lgkmcnt(0)
	v_add_f32_e32 v64, v67, v68
	ds_bpermute_b32 v65, v123, v64
	global_store_dwordx4 v[70:71], v[72:75], off
	v_cvt_pk_bf16_f32 v66, v88, v89
	v_cvt_pk_bf16_f32 v67, v90, v91
	v_cvt_pk_bf16_f32 v68, v92, v93
	v_cvt_pk_bf16_f32 v69, v94, v95
	global_store_dwordx4 v[70:71], v[66:69], off offset:256
	s_and_saveexec_b64 s[36:37], s[4:5]
	s_cbranch_execz .LBB0_1084
	v_lshl_add_u64 v[66:67], v[178:179], 2, s[16:17]
	s_waitcnt lgkmcnt(0)
	v_add_f32_e32 v64, v64, v65
	global_atomic_add_f32 v[66:67], v64, off
.LBB0_1084:
	s_or_b64 exec, exec, s[36:37]
	v_add_u32_e32 v118, 0x80, v208
	v_ashrrev_i32_e32 v119, 31, v118
	s_waitcnt lgkmcnt(0)
	v_lshlrev_b64 v[64:65], 10, v[118:119]
	v_lshl_add_u64 v[64:65], v[64:65], 0, v[176:177]
	v_lshlrev_b64 v[64:65], 1, v[64:65]
	v_lshl_add_u64 v[66:67], s[14:15], 0, v[64:65]
	global_load_dwordx4 v[124:127], v[66:67], off
	v_lshl_add_u64 v[66:67], s[12:13], 0, v[64:65]
	global_load_dwordx4 v[128:131], v[66:67], off
	v_add_u32_e32 v116, 0x90, v208
	v_add_u32_e32 v114, 0xa0, v208
	v_add_u32_e32 v112, 0xb0, v208
	v_ashrrev_i32_e32 v117, 31, v116
	v_fmamk_f32 v72, v228, 0x3a800000, v222
	v_ashrrev_i32_e32 v115, 31, v114
	v_ashrrev_i32_e32 v113, 31, v112
	v_lshlrev_b64 v[66:67], 10, v[116:117]
	v_mul_f32_e32 v73, 0x4b800000, v72
	v_lshlrev_b64 v[68:69], 10, v[114:115]
	v_lshlrev_b64 v[70:71], 10, v[112:113]
	v_cmp_gt_f32_e32 vcc, s65, v72
	v_lshl_add_u64 v[66:67], v[66:67], 0, v[176:177]
	v_lshl_add_u64 v[68:69], v[68:69], 0, v[176:177]
	v_cndmask_b32_e32 v72, v72, v73, vcc
	v_lshl_add_u64 v[70:71], v[70:71], 0, v[176:177]
	v_lshlrev_b64 v[66:67], 1, v[66:67]
	v_rsq_f32_e32 v144, v72
	v_lshlrev_b64 v[68:69], 1, v[68:69]
	v_lshlrev_b64 v[70:71], 1, v[70:71]
	v_or_b32_e32 v64, 0x100, v64
	v_lshl_add_u64 v[72:73], s[12:13], 0, v[66:67]
	v_lshl_add_u64 v[74:75], s[14:15], 0, v[66:67]
	v_or_b32_e32 v66, 0x100, v66
	v_lshl_add_u64 v[76:77], s[12:13], 0, v[68:69]
	v_lshl_add_u64 v[78:79], s[14:15], 0, v[68:69]
	v_or_b32_e32 v68, 0x100, v68
	v_lshl_add_u64 v[80:81], s[12:13], 0, v[70:71]
	v_lshl_add_u64 v[82:83], s[14:15], 0, v[70:71]
	v_lshl_add_u64 v[84:85], s[12:13], 0, v[64:65]
	v_lshl_add_u64 v[86:87], s[12:13], 0, v[66:67]
	v_lshl_add_u64 v[64:65], s[14:15], 0, v[64:65]
	global_load_dwordx4 v[104:107], v[72:73], off
	global_load_dwordx4 v[108:111], v[74:75], off
	v_lshl_add_u64 v[66:67], s[14:15], 0, v[66:67]
	global_load_dwordx4 v[88:91], v[76:77], off
	global_load_dwordx4 v[92:95], v[78:79], off
	v_lshl_add_u64 v[140:141], s[12:13], 0, v[68:69]
	v_lshl_add_u64 v[68:69], s[14:15], 0, v[68:69]
	global_load_dwordx4 v[72:75], v[80:81], off
	global_load_dwordx4 v[76:79], v[82:83], off
	global_load_dwordx4 v[132:135], v[84:85], off
	global_load_dwordx4 v[136:139], v[64:65], off
	global_load_dwordx4 v[96:99], v[86:87], off
	global_load_dwordx4 v[100:103], v[66:67], off
	s_nop 0
	global_load_dwordx4 v[80:83], v[140:141], off
	global_load_dwordx4 v[84:87], v[68:69], off
	v_or_b32_e32 v70, 0x100, v70
	v_lshl_add_u64 v[142:143], s[12:13], 0, v[70:71]
	v_lshl_add_u64 v[70:71], s[14:15], 0, v[70:71]
	v_mul_f32_e32 v64, 0x45800000, v144
	v_cndmask_b32_e32 v140, v144, v64, vcc
	v_mul_f32_e32 v140, 0xbfb8aa3b, v140
	global_load_dwordx4 v[64:67], v[142:143], off
	s_nop 0
	global_load_dwordx4 v[68:71], v[70:71], off
	v_mul_f32_e32 v56, v140, v56
	v_exp_f32_e32 v56, v56
	v_mul_f32_e32 v57, v140, v57
	v_exp_f32_e32 v57, v57
	v_add_f32_e32 v56, 1.0, v56
	v_rcp_f32_e32 v56, v56
	v_mul_f32_e32 v58, v140, v58
	v_exp_f32_e32 v58, v58
	v_mul_f32_e32 v61, v140, v61
	v_mul_f32_e32 v60, v140, v60
	v_exp_f32_e32 v61, v61
	v_mul_f32_e32 v59, v140, v59
	v_exp_f32_e32 v60, v60
	v_exp_f32_e32 v59, v59
	v_mul_f32_e32 v48, v140, v48
	v_add_f32_e32 v61, 1.0, v61
	v_exp_f32_e32 v48, v48
	v_add_f32_e32 v60, 1.0, v60
	v_rcp_f32_e32 v61, v61
	v_rcp_f32_e32 v60, v60
	v_add_f32_e32 v59, 1.0, v59
	v_rcp_f32_e32 v59, v59
	v_mul_f32_e32 v49, v140, v49
	v_add_f32_e32 v48, 1.0, v48
	s_waitcnt vmcnt(15)
	v_lshlrev_b32_e32 v143, 16, v126
	v_and_b32_e32 v126, 0xffff0000, v126
	s_waitcnt vmcnt(14)
	v_lshlrev_b32_e32 v147, 16, v130
	v_fmac_f32_e32 v147, v56, v143
	v_add_f32_e32 v56, 1.0, v57
	v_mul_f32_e32 v57, v140, v62
	v_rcp_f32_e32 v56, v56
	v_exp_f32_e32 v57, v57
	v_and_b32_e32 v130, 0xffff0000, v130
	v_lshlrev_b32_e32 v141, 16, v124
	v_fmac_f32_e32 v130, v56, v126
	v_add_f32_e32 v56, 1.0, v57
	v_add_f32_e32 v57, 1.0, v58
	v_mul_f32_e32 v58, v140, v63
	v_exp_f32_e32 v58, v58
	v_rcp_f32_e32 v56, v56
	v_and_b32_e32 v124, 0xffff0000, v124
	v_lshlrev_b32_e32 v142, 16, v125
	v_add_f32_e32 v58, 1.0, v58
	v_rcp_f32_e32 v58, v58
	v_and_b32_e32 v125, 0xffff0000, v125
	v_lshlrev_b32_e32 v145, 16, v128
	v_and_b32_e32 v128, 0xffff0000, v128
	v_lshlrev_b32_e32 v146, 16, v129
	v_and_b32_e32 v129, 0xffff0000, v129
	v_rcp_f32_e32 v57, v57
	v_fmac_f32_e32 v128, v61, v124
	v_fmac_f32_e32 v129, v58, v125
	v_rcp_f32_e32 v48, v48
	v_exp_f32_e32 v49, v49
	v_lshlrev_b32_e32 v144, 16, v127
	v_and_b32_e32 v127, 0xffff0000, v127
	v_lshlrev_b32_e32 v148, 16, v131
	v_and_b32_e32 v131, 0xffff0000, v131
	v_fmac_f32_e32 v145, v60, v141
	v_fmac_f32_e32 v146, v56, v142
	v_mul_f32_e32 v60, v128, v128
	v_mul_f32_e32 v61, v129, v129
	v_fmac_f32_e32 v131, v59, v127
	v_fmac_f32_e32 v60, v145, v145
	v_fmac_f32_e32 v61, v146, v146
	v_fmac_f32_e32 v148, v57, v144
	v_cvt_pk_bf16_f32 v57, v146, v129
	v_cvt_pk_bf16_f32 v58, v147, v130
	v_cvt_pk_bf16_f32 v59, v148, v131
	v_add_f32_e32 v60, v60, v61
	v_mul_f32_e32 v61, v130, v130
	v_mul_f32_e32 v62, v131, v131
	s_waitcnt vmcnt(6)
	v_lshlrev_b32_e32 v125, 16, v138
	v_lshlrev_b32_e32 v129, 16, v132
	v_and_b32_e32 v130, 0xffff0000, v132
	v_lshlrev_b32_e32 v131, 16, v133
	v_and_b32_e32 v132, 0xffff0000, v133
	v_lshlrev_b32_e32 v133, 16, v134
	v_fmac_f32_e32 v133, v48, v125
	v_add_f32_e32 v48, 1.0, v49
	v_mul_f32_e32 v49, v140, v54
	v_mul_f32_e32 v50, v140, v50
	v_rcp_f32_e32 v48, v48
	v_exp_f32_e32 v49, v49
	v_exp_f32_e32 v50, v50
	v_and_b32_e32 v126, 0xffff0000, v138
	v_and_b32_e32 v134, 0xffff0000, v134
	v_mul_f32_e32 v53, v140, v53
	v_fmac_f32_e32 v134, v48, v126
	v_add_f32_e32 v48, 1.0, v49
	v_add_f32_e32 v49, 1.0, v50
	v_mul_f32_e32 v50, v140, v55
	v_mul_f32_e32 v52, v140, v52
	v_exp_f32_e32 v53, v53
	v_exp_f32_e32 v50, v50
	v_mul_f32_e32 v51, v140, v51
	v_exp_f32_e32 v52, v52
	v_exp_f32_e32 v51, v51
	v_add_f32_e32 v53, 1.0, v53
	v_add_f32_e32 v50, 1.0, v50
	v_add_f32_e32 v52, 1.0, v52
	v_rcp_f32_e32 v53, v53
	v_rcp_f32_e32 v50, v50
	v_rcp_f32_e32 v52, v52
	v_rcp_f32_e32 v48, v48
	v_rcp_f32_e32 v49, v49
	v_add_f32_e32 v51, 1.0, v51
	v_fmac_f32_e32 v61, v147, v147
	v_fmac_f32_e32 v62, v148, v148
	v_rcp_f32_e32 v51, v51
	v_add_f32_e32 v61, v61, v62
	v_and_b32_e32 v62, 0xffff0000, v136
	v_and_b32_e32 v124, 0xffff0000, v137
	v_add_f32_e32 v60, v60, v61
	v_lshlrev_b32_e32 v61, 16, v136
	v_lshlrev_b32_e32 v63, 16, v137
	v_lshlrev_b32_e32 v127, 16, v139
	v_lshlrev_b32_e32 v136, 16, v135
	v_fmac_f32_e32 v130, v53, v62
	v_fmac_f32_e32 v132, v50, v124
	v_cvt_pk_bf16_f32 v56, v145, v128
	v_and_b32_e32 v128, 0xffff0000, v139
	v_and_b32_e32 v135, 0xffff0000, v135
	v_fmac_f32_e32 v129, v52, v61
	v_fmac_f32_e32 v131, v48, v63
	v_fmac_f32_e32 v136, v49, v127
	v_mul_f32_e32 v48, v130, v130
	v_mul_f32_e32 v49, v132, v132
	v_fmac_f32_e32 v135, v51, v128
	v_fmac_f32_e32 v48, v129, v129
	v_fmac_f32_e32 v49, v131, v131
	v_add_f32_e32 v48, v48, v49
	v_mul_f32_e32 v49, v134, v134
	v_mul_f32_e32 v50, v135, v135
	v_fmac_f32_e32 v49, v133, v133
	v_fmac_f32_e32 v50, v136, v136
	v_add_f32_e32 v49, v49, v50
	v_add_f32_e32 v48, v48, v49
	v_add_f32_e32 v51, v60, v48
	ds_bpermute_b32 v52, v122, v51
	v_lshlrev_b64 v[120:121], 11, v[118:119]
	v_lshl_add_u64 v[48:49], s[70:71], 0, v[120:121]
	v_lshl_add_u64 v[54:55], v[176:177], 1, v[48:49]
	global_store_dwordx4 v[54:55], v[56:59], off
	s_waitcnt lgkmcnt(0)
	v_add_f32_e32 v48, v51, v52
	ds_bpermute_b32 v49, v123, v48
	v_cvt_pk_bf16_f32 v50, v129, v130
	v_cvt_pk_bf16_f32 v51, v131, v132
	v_cvt_pk_bf16_f32 v52, v133, v134
	v_cvt_pk_bf16_f32 v53, v136, v135
	global_store_dwordx4 v[54:55], v[50:53], off offset:256
	s_and_saveexec_b64 s[36:37], s[4:5]
	s_cbranch_execz .LBB0_1086
	v_lshl_add_u64 v[50:51], v[118:119], 2, s[16:17]
	s_waitcnt lgkmcnt(0)
	v_add_f32_e32 v48, v48, v49
	global_atomic_add_f32 v[50:51], v48, off
.LBB0_1086:
	s_or_b64 exec, exec, s[36:37]
	v_fmamk_f32 v48, v227, 0x3a800000, v222
	s_waitcnt lgkmcnt(0)
	v_mul_f32_e32 v49, 0x4b800000, v48
	v_cmp_gt_f32_e32 vcc, s65, v48
	v_lshlrev_b32_e32 v55, 16, v110
	v_lshlrev_b32_e32 v63, 16, v106
	v_cndmask_b32_e32 v48, v48, v49, vcc
	v_rsq_f32_e32 v50, v48
	v_and_b32_e32 v56, 0xffff0000, v110
	v_lshlrev_b32_e32 v59, 16, v104
	v_and_b32_e32 v60, 0xffff0000, v104
	v_mul_f32_e32 v52, 0x45800000, v50
	v_cndmask_b32_e32 v50, v50, v52, vcc
	v_mul_f32_e32 v50, 0xbfb8aa3b, v50
	v_mul_f32_e32 v40, v50, v40
	v_exp_f32_e32 v40, v40
	v_mul_f32_e32 v41, v50, v41
	v_exp_f32_e32 v41, v41
	v_add_f32_e32 v40, 1.0, v40
	v_rcp_f32_e32 v40, v40
	v_mul_f32_e32 v42, v50, v42
	v_mul_f32_e32 v45, v50, v45
	v_fmac_f32_e32 v63, v40, v55
	v_add_f32_e32 v40, 1.0, v41
	v_mul_f32_e32 v41, v50, v46
	v_mul_f32_e32 v44, v50, v44
	v_rcp_f32_e32 v40, v40
	v_exp_f32_e32 v41, v41
	v_exp_f32_e32 v42, v42
	v_exp_f32_e32 v45, v45
	v_mul_f32_e32 v32, v50, v32
	v_exp_f32_e32 v44, v44
	v_and_b32_e32 v104, 0xffff0000, v106
	v_exp_f32_e32 v32, v32
	v_fmac_f32_e32 v104, v40, v56
	v_add_f32_e32 v40, 1.0, v41
	v_add_f32_e32 v41, 1.0, v42
	v_mul_f32_e32 v42, v50, v47
	v_add_f32_e32 v45, 1.0, v45
	v_add_f32_e32 v44, 1.0, v44
	v_rcp_f32_e32 v45, v45
	v_exp_f32_e32 v42, v42
	v_mul_f32_e32 v33, v50, v33
	v_rcp_f32_e32 v44, v44
	v_rcp_f32_e32 v40, v40
	v_add_f32_e32 v32, 1.0, v32
	v_rcp_f32_e32 v32, v32
	v_exp_f32_e32 v33, v33
	v_and_b32_e32 v52, 0xffff0000, v108
	v_lshlrev_b32_e32 v51, 16, v108
	v_lshlrev_b32_e32 v53, 16, v109
	v_lshlrev_b32_e32 v61, 16, v105
	v_fmac_f32_e32 v60, v45, v52
	v_add_f32_e32 v42, 1.0, v42
	v_fmac_f32_e32 v59, v44, v51
	v_rcp_f32_e32 v42, v42
	v_fmac_f32_e32 v61, v40, v53
	v_cvt_pk_bf16_f32 v40, v59, v60
	v_mul_f32_e32 v44, v60, v60
	s_waitcnt vmcnt(6)
	v_lshlrev_b32_e32 v52, 16, v102
	v_lshlrev_b32_e32 v60, 16, v98
	v_fmac_f32_e32 v60, v32, v52
	v_add_f32_e32 v32, 1.0, v33
	v_mul_f32_e32 v33, v50, v38
	v_mul_f32_e32 v34, v50, v34
	v_rcp_f32_e32 v41, v41
	v_and_b32_e32 v54, 0xffff0000, v109
	v_and_b32_e32 v62, 0xffff0000, v105
	v_mul_f32_e32 v43, v50, v43
	v_rcp_f32_e32 v32, v32
	v_exp_f32_e32 v33, v33
	v_exp_f32_e32 v34, v34
	v_fmac_f32_e32 v62, v42, v54
	v_lshlrev_b32_e32 v57, 16, v111
	v_lshlrev_b32_e32 v105, 16, v107
	v_exp_f32_e32 v43, v43
	v_mul_f32_e32 v45, v62, v62
	v_fmac_f32_e32 v105, v41, v57
	v_cvt_pk_bf16_f32 v41, v61, v62
	v_fmac_f32_e32 v45, v61, v61
	v_and_b32_e32 v53, 0xffff0000, v102
	v_and_b32_e32 v61, 0xffff0000, v98
	v_mul_f32_e32 v37, v50, v37
	v_fmac_f32_e32 v61, v32, v53
	v_add_f32_e32 v32, 1.0, v33
	v_add_f32_e32 v33, 1.0, v34
	v_mul_f32_e32 v34, v50, v39
	v_mul_f32_e32 v36, v50, v36
	v_add_f32_e32 v43, 1.0, v43
	v_exp_f32_e32 v37, v37
	v_exp_f32_e32 v34, v34
	v_mul_f32_e32 v35, v50, v35
	v_rcp_f32_e32 v43, v43
	v_exp_f32_e32 v36, v36
	v_exp_f32_e32 v35, v35
	v_and_b32_e32 v58, 0xffff0000, v111
	v_and_b32_e32 v106, 0xffff0000, v107
	v_add_f32_e32 v37, 1.0, v37
	v_add_f32_e32 v34, 1.0, v34
	v_fmac_f32_e32 v106, v43, v58
	v_fmac_f32_e32 v44, v59, v59
	v_add_f32_e32 v36, 1.0, v36
	v_rcp_f32_e32 v37, v37
	v_rcp_f32_e32 v34, v34
	v_add_f32_e32 v44, v44, v45
	v_mul_f32_e32 v45, v104, v104
	v_mul_f32_e32 v46, v106, v106
	v_rcp_f32_e32 v36, v36
	v_rcp_f32_e32 v32, v32
	v_rcp_f32_e32 v33, v33
	v_add_f32_e32 v35, 1.0, v35
	v_fmac_f32_e32 v45, v63, v63
	v_fmac_f32_e32 v46, v105, v105
	v_rcp_f32_e32 v35, v35
	v_add_f32_e32 v45, v45, v46
	v_and_b32_e32 v46, 0xffff0000, v100
	v_and_b32_e32 v51, 0xffff0000, v101
	v_and_b32_e32 v57, 0xffff0000, v96
	v_and_b32_e32 v59, 0xffff0000, v97
	v_add_f32_e32 v44, v44, v45
	v_lshlrev_b32_e32 v45, 16, v100
	v_lshlrev_b32_e32 v47, 16, v101
	v_lshlrev_b32_e32 v54, 16, v103
	v_lshlrev_b32_e32 v56, 16, v96
	v_lshlrev_b32_e32 v58, 16, v97
	v_lshlrev_b32_e32 v62, 16, v99
	v_fmac_f32_e32 v57, v37, v46
	v_fmac_f32_e32 v59, v34, v51
	v_cvt_pk_bf16_f32 v42, v63, v104
	v_and_b32_e32 v55, 0xffff0000, v103
	v_and_b32_e32 v63, 0xffff0000, v99
	v_fmac_f32_e32 v56, v36, v45
	v_fmac_f32_e32 v58, v32, v47
	v_fmac_f32_e32 v62, v33, v54
	v_mul_f32_e32 v32, v57, v57
	v_mul_f32_e32 v33, v59, v59
	v_fmac_f32_e32 v63, v35, v55
	v_fmac_f32_e32 v32, v56, v56
	v_fmac_f32_e32 v33, v58, v58
	v_add_f32_e32 v32, v32, v33
	v_mul_f32_e32 v33, v61, v61
	v_mul_f32_e32 v34, v63, v63
	v_fmac_f32_e32 v33, v60, v60
	v_fmac_f32_e32 v34, v62, v62
	v_add_f32_e32 v33, v33, v34
	v_add_f32_e32 v32, v32, v33
	v_add_f32_e32 v35, v44, v32
	ds_bpermute_b32 v36, v122, v35
	v_lshlrev_b64 v[48:49], 11, v[116:117]
	v_lshl_add_u64 v[32:33], s[70:71], 0, v[48:49]
	v_lshl_add_u64 v[38:39], v[176:177], 1, v[32:33]
	v_cvt_pk_bf16_f32 v43, v105, v106
	s_waitcnt lgkmcnt(0)
	v_add_f32_e32 v32, v35, v36
	ds_bpermute_b32 v33, v123, v32
	global_store_dwordx4 v[38:39], v[40:43], off
	v_cvt_pk_bf16_f32 v34, v56, v57
	v_cvt_pk_bf16_f32 v35, v58, v59
	v_cvt_pk_bf16_f32 v36, v60, v61
	v_cvt_pk_bf16_f32 v37, v62, v63
	global_store_dwordx4 v[38:39], v[34:37], off offset:256
	s_and_saveexec_b64 s[36:37], s[4:5]
	s_cbranch_execz .LBB0_1088
	v_lshl_add_u64 v[34:35], v[116:117], 2, s[16:17]
	s_waitcnt lgkmcnt(0)
	v_add_f32_e32 v32, v32, v33
	global_atomic_add_f32 v[34:35], v32, off
.LBB0_1088:
	s_or_b64 exec, exec, s[36:37]
	v_fmamk_f32 v32, v226, 0x3a800000, v222
	s_waitcnt lgkmcnt(0)
	v_mul_f32_e32 v33, 0x4b800000, v32
	v_cmp_gt_f32_e32 vcc, s65, v32
	v_lshlrev_b32_e32 v39, 16, v94
	v_lshlrev_b32_e32 v47, 16, v90
	v_cndmask_b32_e32 v32, v32, v33, vcc
	v_rsq_f32_e32 v34, v32
	v_and_b32_e32 v40, 0xffff0000, v94
	v_and_b32_e32 v48, 0xffff0000, v90
	v_and_b32_e32 v44, 0xffff0000, v88
	v_mul_f32_e32 v36, 0x45800000, v34
	v_cndmask_b32_e32 v34, v34, v36, vcc
	v_mul_f32_e32 v34, 0xbfb8aa3b, v34
	v_mul_f32_e32 v24, v34, v24
	v_exp_f32_e32 v24, v24
	v_mul_f32_e32 v25, v34, v25
	v_exp_f32_e32 v25, v25
	v_add_f32_e32 v24, 1.0, v24
	v_rcp_f32_e32 v24, v24
	v_mul_f32_e32 v26, v34, v26
	v_mul_f32_e32 v29, v34, v29
	v_fmac_f32_e32 v47, v24, v39
	v_add_f32_e32 v24, 1.0, v25
	v_mul_f32_e32 v25, v34, v30
	v_mul_f32_e32 v28, v34, v28
	v_rcp_f32_e32 v24, v24
	v_exp_f32_e32 v25, v25
	v_exp_f32_e32 v26, v26
	v_exp_f32_e32 v29, v29
	v_mul_f32_e32 v16, v34, v16
	v_exp_f32_e32 v28, v28
	v_exp_f32_e32 v16, v16
	v_fmac_f32_e32 v48, v24, v40
	v_add_f32_e32 v24, 1.0, v25
	v_add_f32_e32 v25, 1.0, v26
	v_mul_f32_e32 v26, v34, v31
	v_add_f32_e32 v29, 1.0, v29
	v_add_f32_e32 v28, 1.0, v28
	v_rcp_f32_e32 v29, v29
	v_exp_f32_e32 v26, v26
	v_mul_f32_e32 v17, v34, v17
	v_rcp_f32_e32 v28, v28
	v_rcp_f32_e32 v24, v24
	v_add_f32_e32 v16, 1.0, v16
	v_rcp_f32_e32 v16, v16
	v_exp_f32_e32 v17, v17
	v_and_b32_e32 v36, 0xffff0000, v92
	v_lshlrev_b32_e32 v35, 16, v92
	v_lshlrev_b32_e32 v37, 16, v93
	v_lshlrev_b32_e32 v43, 16, v88
	v_lshlrev_b32_e32 v45, 16, v89
	v_fmac_f32_e32 v44, v29, v36
	v_add_f32_e32 v26, 1.0, v26
	v_fmac_f32_e32 v43, v28, v35
	v_rcp_f32_e32 v26, v26
	v_fmac_f32_e32 v45, v24, v37
	v_cvt_pk_bf16_f32 v24, v43, v44
	v_mul_f32_e32 v28, v44, v44
	s_waitcnt vmcnt(6)
	v_lshlrev_b32_e32 v36, 16, v86
	v_lshlrev_b32_e32 v44, 16, v82
	v_fmac_f32_e32 v44, v16, v36
	v_add_f32_e32 v16, 1.0, v17
	v_mul_f32_e32 v17, v34, v22
	v_mul_f32_e32 v18, v34, v18
	v_rcp_f32_e32 v25, v25
	v_and_b32_e32 v38, 0xffff0000, v93
	v_and_b32_e32 v46, 0xffff0000, v89
	v_mul_f32_e32 v27, v34, v27
	v_rcp_f32_e32 v16, v16
	v_exp_f32_e32 v17, v17
	v_exp_f32_e32 v18, v18
	v_fmac_f32_e32 v46, v26, v38
	v_lshlrev_b32_e32 v41, 16, v95
	v_lshlrev_b32_e32 v49, 16, v91
	v_exp_f32_e32 v27, v27
	v_mul_f32_e32 v29, v46, v46
	v_fmac_f32_e32 v49, v25, v41
	v_cvt_pk_bf16_f32 v25, v45, v46
	v_fmac_f32_e32 v29, v45, v45
	v_and_b32_e32 v37, 0xffff0000, v86
	v_and_b32_e32 v45, 0xffff0000, v82
	v_mul_f32_e32 v21, v34, v21
	v_fmac_f32_e32 v45, v16, v37
	v_add_f32_e32 v16, 1.0, v17
	v_add_f32_e32 v17, 1.0, v18
	v_mul_f32_e32 v18, v34, v23
	v_mul_f32_e32 v20, v34, v20
	v_add_f32_e32 v27, 1.0, v27
	v_exp_f32_e32 v21, v21
	v_exp_f32_e32 v18, v18
	v_mul_f32_e32 v19, v34, v19
	v_rcp_f32_e32 v27, v27
	v_exp_f32_e32 v20, v20
	v_exp_f32_e32 v19, v19
	v_and_b32_e32 v42, 0xffff0000, v95
	v_and_b32_e32 v50, 0xffff0000, v91
	v_add_f32_e32 v21, 1.0, v21
	v_add_f32_e32 v18, 1.0, v18
	v_fmac_f32_e32 v50, v27, v42
	v_fmac_f32_e32 v28, v43, v43
	v_add_f32_e32 v20, 1.0, v20
	v_rcp_f32_e32 v21, v21
	v_rcp_f32_e32 v18, v18
	v_add_f32_e32 v28, v28, v29
	v_mul_f32_e32 v29, v48, v48
	v_mul_f32_e32 v30, v50, v50
	v_rcp_f32_e32 v20, v20
	v_rcp_f32_e32 v16, v16
	v_rcp_f32_e32 v17, v17
	v_add_f32_e32 v19, 1.0, v19
	v_fmac_f32_e32 v29, v47, v47
	v_fmac_f32_e32 v30, v49, v49
	v_rcp_f32_e32 v19, v19
	v_add_f32_e32 v29, v29, v30
	v_and_b32_e32 v30, 0xffff0000, v84
	v_and_b32_e32 v35, 0xffff0000, v85
	v_and_b32_e32 v41, 0xffff0000, v80
	v_and_b32_e32 v43, 0xffff0000, v81
	v_add_f32_e32 v28, v28, v29
	v_lshlrev_b32_e32 v29, 16, v84
	v_lshlrev_b32_e32 v31, 16, v85
	v_lshlrev_b32_e32 v38, 16, v87
	v_lshlrev_b32_e32 v40, 16, v80
	v_lshlrev_b32_e32 v42, 16, v81
	v_lshlrev_b32_e32 v46, 16, v83
	v_fmac_f32_e32 v41, v21, v30
	v_fmac_f32_e32 v43, v18, v35
	v_cvt_pk_bf16_f32 v26, v47, v48
	v_and_b32_e32 v39, 0xffff0000, v87
	v_and_b32_e32 v47, 0xffff0000, v83
	v_fmac_f32_e32 v40, v20, v29
	v_fmac_f32_e32 v42, v16, v31
	v_fmac_f32_e32 v46, v17, v38
	v_mul_f32_e32 v16, v41, v41
	v_mul_f32_e32 v17, v43, v43
	v_fmac_f32_e32 v47, v19, v39
	v_fmac_f32_e32 v16, v40, v40
	v_fmac_f32_e32 v17, v42, v42
	v_add_f32_e32 v16, v16, v17
	v_mul_f32_e32 v17, v45, v45
	v_mul_f32_e32 v18, v47, v47
	v_fmac_f32_e32 v17, v44, v44
	v_fmac_f32_e32 v18, v46, v46
	v_add_f32_e32 v17, v17, v18
	v_add_f32_e32 v16, v16, v17
	v_add_f32_e32 v19, v28, v16
	ds_bpermute_b32 v20, v122, v19
	v_lshlrev_b64 v[32:33], 11, v[114:115]
	v_lshl_add_u64 v[16:17], s[70:71], 0, v[32:33]
	v_lshl_add_u64 v[22:23], v[176:177], 1, v[16:17]
	v_cvt_pk_bf16_f32 v27, v49, v50
	s_waitcnt lgkmcnt(0)
	v_add_f32_e32 v16, v19, v20
	ds_bpermute_b32 v17, v123, v16
	global_store_dwordx4 v[22:23], v[24:27], off
	v_cvt_pk_bf16_f32 v18, v40, v41
	v_cvt_pk_bf16_f32 v19, v42, v43
	v_cvt_pk_bf16_f32 v20, v44, v45
	v_cvt_pk_bf16_f32 v21, v46, v47
	global_store_dwordx4 v[22:23], v[18:21], off offset:256
	s_and_saveexec_b64 s[36:37], s[4:5]
	s_cbranch_execz .LBB0_1090
	v_lshl_add_u64 v[18:19], v[114:115], 2, s[16:17]
	s_waitcnt lgkmcnt(0)
	v_add_f32_e32 v16, v16, v17
	global_atomic_add_f32 v[18:19], v16, off
.LBB0_1090:
	s_or_b64 exec, exec, s[36:37]
	v_fmamk_f32 v16, v225, 0x3a800000, v222
	s_waitcnt lgkmcnt(0)
	v_mul_f32_e32 v17, 0x4b800000, v16
	v_cmp_gt_f32_e32 vcc, s65, v16
	v_lshlrev_b32_e32 v23, 16, v78
	v_lshlrev_b32_e32 v31, 16, v74
	v_cndmask_b32_e32 v16, v16, v17, vcc
	v_rsq_f32_e32 v18, v16
	v_and_b32_e32 v24, 0xffff0000, v78
	v_and_b32_e32 v32, 0xffff0000, v74
	v_and_b32_e32 v28, 0xffff0000, v72
	v_mul_f32_e32 v20, 0x45800000, v18
	v_cndmask_b32_e32 v18, v18, v20, vcc
	v_mul_f32_e32 v18, 0xbfb8aa3b, v18
	v_mul_f32_e32 v8, v18, v8
	v_exp_f32_e32 v8, v8
	v_mul_f32_e32 v9, v18, v9
	v_exp_f32_e32 v9, v9
	v_add_f32_e32 v8, 1.0, v8
	v_rcp_f32_e32 v8, v8
	v_mul_f32_e32 v10, v18, v10
	v_mul_f32_e32 v13, v18, v13
	v_fmac_f32_e32 v31, v8, v23
	v_add_f32_e32 v8, 1.0, v9
	v_mul_f32_e32 v9, v18, v14
	v_mul_f32_e32 v12, v18, v12
	v_rcp_f32_e32 v8, v8
	v_exp_f32_e32 v9, v9
	v_exp_f32_e32 v10, v10
	v_exp_f32_e32 v13, v13
	v_mul_f32_e32 v0, v18, v0
	v_exp_f32_e32 v12, v12
	v_exp_f32_e32 v0, v0
	v_fmac_f32_e32 v32, v8, v24
	v_add_f32_e32 v8, 1.0, v9
	v_add_f32_e32 v9, 1.0, v10
	v_mul_f32_e32 v10, v18, v15
	v_add_f32_e32 v13, 1.0, v13
	v_add_f32_e32 v12, 1.0, v12
	v_rcp_f32_e32 v13, v13
	v_exp_f32_e32 v10, v10
	v_mul_f32_e32 v1, v18, v1
	v_rcp_f32_e32 v12, v12
	v_rcp_f32_e32 v8, v8
	v_add_f32_e32 v0, 1.0, v0
	v_rcp_f32_e32 v0, v0
	v_exp_f32_e32 v1, v1
	v_and_b32_e32 v20, 0xffff0000, v76
	v_lshlrev_b32_e32 v19, 16, v76
	v_lshlrev_b32_e32 v21, 16, v77
	v_lshlrev_b32_e32 v27, 16, v72
	v_lshlrev_b32_e32 v29, 16, v73
	v_fmac_f32_e32 v28, v13, v20
	v_add_f32_e32 v10, 1.0, v10
	v_fmac_f32_e32 v27, v12, v19
	v_rcp_f32_e32 v10, v10
	v_fmac_f32_e32 v29, v8, v21
	v_cvt_pk_bf16_f32 v8, v27, v28
	v_mul_f32_e32 v12, v28, v28
	s_waitcnt vmcnt(6)
	v_lshlrev_b32_e32 v20, 16, v70
	v_lshlrev_b32_e32 v28, 16, v66
	v_fmac_f32_e32 v28, v0, v20
	v_add_f32_e32 v0, 1.0, v1
	v_mul_f32_e32 v1, v18, v6
	v_mul_f32_e32 v2, v18, v2
	v_rcp_f32_e32 v9, v9
	v_and_b32_e32 v22, 0xffff0000, v77
	v_and_b32_e32 v30, 0xffff0000, v73
	v_mul_f32_e32 v11, v18, v11
	v_rcp_f32_e32 v0, v0
	v_exp_f32_e32 v1, v1
	v_exp_f32_e32 v2, v2
	v_fmac_f32_e32 v30, v10, v22
	v_lshlrev_b32_e32 v25, 16, v79
	v_lshlrev_b32_e32 v33, 16, v75
	v_exp_f32_e32 v11, v11
	v_mul_f32_e32 v13, v30, v30
	v_fmac_f32_e32 v33, v9, v25
	v_cvt_pk_bf16_f32 v9, v29, v30
	v_fmac_f32_e32 v13, v29, v29
	v_and_b32_e32 v21, 0xffff0000, v70
	v_and_b32_e32 v29, 0xffff0000, v66
	v_mul_f32_e32 v5, v18, v5
	v_fmac_f32_e32 v29, v0, v21
	v_add_f32_e32 v0, 1.0, v1
	v_add_f32_e32 v1, 1.0, v2
	v_mul_f32_e32 v2, v18, v7
	v_mul_f32_e32 v4, v18, v4
	v_add_f32_e32 v11, 1.0, v11
	v_exp_f32_e32 v5, v5
	v_exp_f32_e32 v2, v2
	v_mul_f32_e32 v3, v18, v3
	v_rcp_f32_e32 v11, v11
	v_exp_f32_e32 v4, v4
	v_exp_f32_e32 v3, v3
	v_and_b32_e32 v26, 0xffff0000, v79
	v_and_b32_e32 v34, 0xffff0000, v75
	v_add_f32_e32 v5, 1.0, v5
	v_add_f32_e32 v2, 1.0, v2
	v_fmac_f32_e32 v34, v11, v26
	v_fmac_f32_e32 v12, v27, v27
	v_add_f32_e32 v4, 1.0, v4
	v_rcp_f32_e32 v5, v5
	v_rcp_f32_e32 v2, v2
	v_add_f32_e32 v12, v12, v13
	v_mul_f32_e32 v13, v32, v32
	v_mul_f32_e32 v14, v34, v34
	v_rcp_f32_e32 v4, v4
	v_rcp_f32_e32 v0, v0
	v_rcp_f32_e32 v1, v1
	v_add_f32_e32 v3, 1.0, v3
	v_fmac_f32_e32 v13, v31, v31
	v_fmac_f32_e32 v14, v33, v33
	v_rcp_f32_e32 v3, v3
	v_add_f32_e32 v13, v13, v14
	v_and_b32_e32 v14, 0xffff0000, v68
	v_and_b32_e32 v19, 0xffff0000, v69
	v_and_b32_e32 v25, 0xffff0000, v64
	v_and_b32_e32 v27, 0xffff0000, v65
	v_add_f32_e32 v12, v12, v13
	v_lshlrev_b32_e32 v13, 16, v68
	v_lshlrev_b32_e32 v15, 16, v69
	v_lshlrev_b32_e32 v22, 16, v71
	v_lshlrev_b32_e32 v24, 16, v64
	v_lshlrev_b32_e32 v26, 16, v65
	v_lshlrev_b32_e32 v30, 16, v67
	v_fmac_f32_e32 v25, v5, v14
	v_fmac_f32_e32 v27, v2, v19
	v_cvt_pk_bf16_f32 v10, v31, v32
	v_and_b32_e32 v23, 0xffff0000, v71
	v_and_b32_e32 v31, 0xffff0000, v67
	v_fmac_f32_e32 v24, v4, v13
	v_fmac_f32_e32 v26, v0, v15
	v_fmac_f32_e32 v30, v1, v22
	v_mul_f32_e32 v0, v25, v25
	v_mul_f32_e32 v1, v27, v27
	v_fmac_f32_e32 v31, v3, v23
	v_fmac_f32_e32 v0, v24, v24
	v_fmac_f32_e32 v1, v26, v26
	v_add_f32_e32 v0, v0, v1
	v_mul_f32_e32 v1, v29, v29
	v_mul_f32_e32 v2, v31, v31
	v_fmac_f32_e32 v1, v28, v28
	v_fmac_f32_e32 v2, v30, v30
	v_add_f32_e32 v1, v1, v2
	v_add_f32_e32 v0, v0, v1
	v_add_f32_e32 v3, v12, v0
	ds_bpermute_b32 v4, v122, v3
	v_lshlrev_b64 v[16:17], 11, v[112:113]
	v_lshl_add_u64 v[0:1], s[70:71], 0, v[16:17]
	v_lshl_add_u64 v[6:7], v[176:177], 1, v[0:1]
	v_cvt_pk_bf16_f32 v11, v33, v34
	s_waitcnt lgkmcnt(0)
	v_add_f32_e32 v0, v3, v4
	ds_bpermute_b32 v1, v123, v0
	global_store_dwordx4 v[6:7], v[8:11], off
	v_cvt_pk_bf16_f32 v2, v24, v25
	v_cvt_pk_bf16_f32 v3, v26, v27
	v_cvt_pk_bf16_f32 v4, v28, v29
	v_cvt_pk_bf16_f32 v5, v30, v31
	global_store_dwordx4 v[6:7], v[2:5], off offset:256
	s_and_saveexec_b64 s[36:37], s[4:5]
	s_cbranch_execz .LBB0_1092
	v_lshl_add_u64 v[2:3], v[112:113], 2, s[16:17]
	s_waitcnt lgkmcnt(0)
	v_add_f32_e32 v0, v0, v1
	global_atomic_add_f32 v[2:3], v0, off

.LBB0_1520:
	v_lshl_or_b32 v124, s61, 8, v220
	v_ashrrev_i32_e32 v125, 31, v124
	v_lshlrev_b64 v[126:127], 10, v[206:207]
	v_lshl_add_u64 v[184:185], v[126:127], 0, v[124:125]
	v_lshlrev_b64 v[126:127], 1, v[184:185]
	v_lshl_add_u64 v[128:129], s[14:15], 0, v[126:127]
	global_load_dwordx4 v[208:211], v[128:129], off
	v_lshl_add_u64 v[128:129], s[12:13], 0, v[126:127]
	global_load_dwordx4 v[212:215], v[128:129], off
	v_or_b32_e32 v128, 16, v206
	v_or_b32_e32 v130, 32, v206
	v_or_b32_e32 v136, 48, v206
	v_ashrrev_i32_e32 v129, 31, v128
	s_waitcnt vmcnt(0)
	v_fmamk_f32 v138, v230, 0x3a800000, v221
	v_ashrrev_i32_e32 v131, 31, v130
	v_ashrrev_i32_e32 v137, 31, v136
	v_lshlrev_b64 v[128:129], 10, v[128:129]
	v_mul_f32_e32 v139, 0x4b800000, v138
	v_lshlrev_b64 v[130:131], 10, v[130:131]
	v_lshlrev_b64 v[136:137], 10, v[136:137]
	v_cmp_gt_f32_e32 vcc, s60, v138
	v_lshl_add_u64 v[190:191], v[128:129], 0, v[124:125]
	v_or_b32_e32 v126, 0x100, v126
	v_cndmask_b32_e32 v138, v138, v139, vcc
	v_lshl_add_u64 v[188:189], v[130:131], 0, v[124:125]
	v_lshl_add_u64 v[186:187], v[136:137], 0, v[124:125]
	v_lshlrev_b64 v[124:125], 1, v[190:191]
	v_lshl_add_u64 v[136:137], s[12:13], 0, v[126:127]
	v_rsq_f32_e32 v216, v138
	v_lshl_add_u64 v[126:127], s[14:15], 0, v[126:127]
	v_lshl_add_u64 v[138:139], s[12:13], 0, v[124:125]
	v_lshl_add_u64 v[140:141], s[14:15], 0, v[124:125]
	global_load_dwordx4 v[176:179], v[136:137], off
	global_load_dwordx4 v[180:183], v[126:127], off
	global_load_dwordx4 v[168:171], v[138:139], off
	global_load_dwordx4 v[172:175], v[140:141], off
	v_lshlrev_b64 v[128:129], 1, v[188:189]
	v_lshlrev_b64 v[130:131], 1, v[186:187]
	v_or_b32_e32 v124, 0x100, v124
	v_lshl_add_u64 v[142:143], s[12:13], 0, v[128:129]
	v_lshl_add_u64 v[144:145], s[14:15], 0, v[128:129]
	v_or_b32_e32 v128, 0x100, v128
	v_lshl_add_u64 v[146:147], s[12:13], 0, v[130:131]
	v_lshl_add_u64 v[148:149], s[14:15], 0, v[130:131]
	v_or_b32_e32 v130, 0x100, v130
	v_lshl_add_u64 v[126:127], s[12:13], 0, v[124:125]
	v_lshl_add_u64 v[124:125], s[14:15], 0, v[124:125]
	global_load_dwordx4 v[152:155], v[142:143], off
	global_load_dwordx4 v[156:159], v[144:145], off
	v_lshl_add_u64 v[144:145], s[12:13], 0, v[128:129]
	v_lshl_add_u64 v[128:129], s[14:15], 0, v[128:129]
	v_lshl_add_u64 v[206:207], s[12:13], 0, v[130:131]
	v_lshl_add_u64 v[130:131], s[14:15], 0, v[130:131]
	global_load_dwordx4 v[136:139], v[146:147], off
	global_load_dwordx4 v[140:143], v[148:149], off
	global_load_dwordx4 v[160:163], v[126:127], off
	global_load_dwordx4 v[164:167], v[124:125], off
	s_nop 0
	global_load_dwordx4 v[144:147], v[144:145], off
	s_nop 0
	global_load_dwordx4 v[148:151], v[128:129], off
	global_load_dwordx4 v[124:127], v[206:207], off
	s_nop 0
	global_load_dwordx4 v[128:131], v[130:131], off
	v_mul_f32_e32 v206, 0x45800000, v216
	v_cndmask_b32_e32 v231, v216, v206, vcc
	v_mul_f32_e32 v231, 0xbfb8aa3b, v231
	v_mul_f32_e32 v132, v231, v132
	v_mul_f32_e32 v133, v231, v133
	v_mul_f32_e32 v120, v231, v120
	v_mul_f32_e32 v121, v231, v121
	v_exp_f32_e32 v132, v132
	v_exp_f32_e32 v133, v133
	v_exp_f32_e32 v120, v120
	v_exp_f32_e32 v121, v121
	v_mul_f32_e32 v122, v231, v122
	v_add_f32_e32 v132, 1.0, v132
	v_add_f32_e32 v133, 1.0, v133
	v_mul_f32_e32 v135, v231, v135
	v_add_f32_e32 v206, 1.0, v120
	v_add_f32_e32 v232, 1.0, v121
	v_rcp_f32_e32 v120, v132
	v_rcp_f32_e32 v121, v133
	v_exp_f32_e32 v122, v122
	v_rcp_f32_e32 v132, v206
	v_rcp_f32_e32 v133, v232
	v_mul_f32_e32 v134, v231, v134
	v_exp_f32_e32 v135, v135
	v_exp_f32_e32 v134, v134
	v_add_f32_e32 v122, 1.0, v122
	v_mul_f32_e32 v112, v231, v112
	v_add_f32_e32 v134, 1.0, v134
	v_lshlrev_b32_e32 v206, 16, v208
	v_and_b32_e32 v207, 0xffff0000, v208
	v_lshlrev_b32_e32 v216, 16, v212
	v_and_b32_e32 v217, 0xffff0000, v212
	v_pk_fma_f32 v[120:121], v[120:121], v[206:207], v[216:217]
	v_lshlrev_b32_e32 v206, 16, v210
	v_and_b32_e32 v207, 0xffff0000, v210
	v_lshlrev_b32_e32 v216, 16, v214
	v_and_b32_e32 v217, 0xffff0000, v214
	v_pk_fma_f32 v[132:133], v[132:133], v[206:207], v[216:217]
	v_rcp_f32_e32 v206, v122
	v_add_f32_e32 v122, 1.0, v135
	v_rcp_f32_e32 v135, v122
	v_mul_f32_e32 v122, v231, v123
	v_rcp_f32_e32 v134, v134
	v_exp_f32_e32 v207, v122
	v_lshlrev_b32_e32 v208, 16, v209
	v_and_b32_e32 v209, 0xffff0000, v209
	v_lshlrev_b32_e32 v122, 16, v213
	v_and_b32_e32 v123, 0xffff0000, v213
	v_pk_fma_f32 v[122:123], v[134:135], v[208:209], v[122:123]
	v_add_f32_e32 v134, 1.0, v207
	v_mul_f32_e32 v117, v231, v117
	v_rcp_f32_e32 v207, v134
	v_exp_f32_e32 v112, v112
	v_mul_f32_e32 v116, v231, v116
	v_exp_f32_e32 v117, v117
	v_lshlrev_b32_e32 v134, 16, v211
	v_and_b32_e32 v135, 0xffff0000, v211
	v_lshlrev_b32_e32 v208, 16, v215
	v_and_b32_e32 v209, 0xffff0000, v215
	v_exp_f32_e32 v116, v116
	v_pk_fma_f32 v[134:135], v[206:207], v[134:135], v[208:209]
	v_lshl_add_u64 v[206:207], v[184:185], 2, s[70:71]
	v_add_f32_e32 v112, 1.0, v112
	global_store_dwordx4 v[206:207], v[120:123], off nt
	global_store_dwordx4 v[206:207], v[132:135], off offset:16 nt
	v_add_f32_e32 v116, 1.0, v116
	v_rcp_f32_e32 v120, v112
	v_add_f32_e32 v112, 1.0, v117
	v_rcp_f32_e32 v117, v112
	v_mul_f32_e32 v112, v231, v113
	v_rcp_f32_e32 v116, v116
	v_exp_f32_e32 v121, v112
	v_mul_f32_e32 v114, v231, v114
	s_waitcnt vmcnt(14)
	v_lshlrev_b32_e32 v122, 16, v180
	v_and_b32_e32 v123, 0xffff0000, v180
	v_lshlrev_b32_e32 v112, 16, v176
	v_and_b32_e32 v113, 0xffff0000, v176
	v_mul_f32_e32 v118, v231, v118
	v_mul_f32_e32 v119, v231, v119
	v_pk_fma_f32 v[112:113], v[116:117], v[122:123], v[112:113]
	v_add_f32_e32 v116, 1.0, v121
	v_exp_f32_e32 v114, v114
	v_rcp_f32_e32 v121, v116
	v_exp_f32_e32 v118, v118
	v_exp_f32_e32 v119, v119
	v_lshlrev_b32_e32 v116, 16, v182
	v_and_b32_e32 v117, 0xffff0000, v182
	v_lshlrev_b32_e32 v122, 16, v178
	v_and_b32_e32 v123, 0xffff0000, v178
	v_add_f32_e32 v114, 1.0, v114
	v_pk_fma_f32 v[116:117], v[120:121], v[116:117], v[122:123]
	v_add_f32_e32 v118, 1.0, v118
	v_rcp_f32_e32 v120, v114
	v_add_f32_e32 v114, 1.0, v119
	v_rcp_f32_e32 v118, v118
	v_rcp_f32_e32 v119, v114
	v_mul_f32_e32 v114, v231, v115
	v_lshlrev_b32_e32 v122, 16, v181
	v_and_b32_e32 v123, 0xffff0000, v181
	v_exp_f32_e32 v121, v114
	v_lshlrev_b32_e32 v114, 16, v177
	v_and_b32_e32 v115, 0xffff0000, v177
	v_pk_fma_f32 v[114:115], v[118:119], v[122:123], v[114:115]
	v_fmamk_f32 v119, v229, 0x3a800000, v221
	v_mul_f32_e32 v122, 0x4b800000, v119
	v_cmp_gt_f32_e32 vcc, s60, v119
	v_add_f32_e32 v118, 1.0, v121
	v_rcp_f32_e32 v121, v118
	v_cndmask_b32_e32 v119, v119, v122, vcc
	v_rsq_f32_e32 v132, v119
	v_lshlrev_b32_e32 v118, 16, v183
	v_and_b32_e32 v119, 0xffff0000, v183
	v_lshlrev_b32_e32 v122, 16, v179
	v_mul_f32_e32 v133, 0x45800000, v132
	v_cndmask_b32_e32 v132, v132, v133, vcc
	v_mul_f32_e32 v132, 0xbfb8aa3b, v132
	v_mul_f32_e32 v104, v132, v104
	v_mul_f32_e32 v109, v132, v109
	v_exp_f32_e32 v104, v104
	v_mul_f32_e32 v108, v132, v108
	v_exp_f32_e32 v109, v109
	v_exp_f32_e32 v108, v108
	v_and_b32_e32 v123, 0xffff0000, v179
	v_add_f32_e32 v104, 1.0, v104
	v_pk_fma_f32 v[118:119], v[120:121], v[118:119], v[122:123]
	global_store_dwordx4 v[206:207], v[112:115], off offset:512 nt
	global_store_dwordx4 v[206:207], v[116:119], off offset:528 nt
	v_add_f32_e32 v108, 1.0, v108
	v_rcp_f32_e32 v112, v104
	v_add_f32_e32 v104, 1.0, v109
	v_rcp_f32_e32 v109, v104
	v_mul_f32_e32 v104, v132, v105
	v_rcp_f32_e32 v108, v108
	v_exp_f32_e32 v113, v104
	v_mul_f32_e32 v106, v132, v106
	s_waitcnt vmcnt(14)
	v_lshlrev_b32_e32 v114, 16, v172
	v_and_b32_e32 v115, 0xffff0000, v172
	v_lshlrev_b32_e32 v104, 16, v168
	v_and_b32_e32 v105, 0xffff0000, v168
	v_mul_f32_e32 v111, v132, v111
	v_pk_fma_f32 v[104:105], v[108:109], v[114:115], v[104:105]
	v_add_f32_e32 v108, 1.0, v113
	v_exp_f32_e32 v106, v106
	v_rcp_f32_e32 v113, v108
	v_mul_f32_e32 v110, v132, v110
	v_exp_f32_e32 v111, v111
	v_exp_f32_e32 v110, v110
	v_lshlrev_b32_e32 v108, 16, v174
	v_and_b32_e32 v109, 0xffff0000, v174
	v_lshlrev_b32_e32 v114, 16, v170
	v_and_b32_e32 v115, 0xffff0000, v170
	v_add_f32_e32 v106, 1.0, v106
	v_pk_fma_f32 v[108:109], v[112:113], v[108:109], v[114:115]
	v_rcp_f32_e32 v112, v106
	v_add_f32_e32 v106, 1.0, v111
	v_rcp_f32_e32 v111, v106
	v_mul_f32_e32 v106, v132, v107
	v_add_f32_e32 v110, 1.0, v110
	v_rcp_f32_e32 v110, v110
	v_exp_f32_e32 v113, v106
	v_lshlrev_b32_e32 v114, 16, v173
	v_and_b32_e32 v115, 0xffff0000, v173
	v_lshlrev_b32_e32 v106, 16, v169
	v_and_b32_e32 v107, 0xffff0000, v169
	v_mul_f32_e32 v96, v132, v96
	v_pk_fma_f32 v[106:107], v[110:111], v[114:115], v[106:107]
	v_add_f32_e32 v110, 1.0, v113
	v_mul_f32_e32 v101, v132, v101
	v_rcp_f32_e32 v113, v110
	v_exp_f32_e32 v96, v96
	v_mul_f32_e32 v100, v132, v100
	v_exp_f32_e32 v101, v101
	v_lshlrev_b32_e32 v110, 16, v175
	v_and_b32_e32 v111, 0xffff0000, v175
	v_lshlrev_b32_e32 v114, 16, v171
	v_and_b32_e32 v115, 0xffff0000, v171
	v_exp_f32_e32 v100, v100
	v_pk_fma_f32 v[110:111], v[112:113], v[110:111], v[114:115]
	v_lshl_add_u64 v[112:113], v[190:191], 2, s[70:71]
	v_add_f32_e32 v96, 1.0, v96
	global_store_dwordx4 v[112:113], v[104:107], off nt
	global_store_dwordx4 v[112:113], v[108:111], off offset:16 nt
	v_add_f32_e32 v100, 1.0, v100
	v_rcp_f32_e32 v104, v96
	v_add_f32_e32 v96, 1.0, v101
	v_rcp_f32_e32 v101, v96
	v_mul_f32_e32 v96, v132, v97
	v_rcp_f32_e32 v100, v100
	v_exp_f32_e32 v105, v96
	v_mul_f32_e32 v98, v132, v98
	s_waitcnt vmcnt(10)
	v_lshlrev_b32_e32 v106, 16, v164
	v_and_b32_e32 v107, 0xffff0000, v164
	v_lshlrev_b32_e32 v96, 16, v160
	v_and_b32_e32 v97, 0xffff0000, v160
	v_mul_f32_e32 v102, v132, v102
	v_mul_f32_e32 v103, v132, v103
	v_pk_fma_f32 v[96:97], v[100:101], v[106:107], v[96:97]
	v_add_f32_e32 v100, 1.0, v105
	v_exp_f32_e32 v98, v98
	v_rcp_f32_e32 v105, v100
	v_exp_f32_e32 v102, v102
	v_exp_f32_e32 v103, v103
	v_lshlrev_b32_e32 v100, 16, v166
	v_and_b32_e32 v101, 0xffff0000, v166
	v_lshlrev_b32_e32 v106, 16, v162
	v_and_b32_e32 v107, 0xffff0000, v162
	v_add_f32_e32 v98, 1.0, v98
	v_pk_fma_f32 v[100:101], v[104:105], v[100:101], v[106:107]
	v_add_f32_e32 v102, 1.0, v102
	v_rcp_f32_e32 v104, v98
	v_add_f32_e32 v98, 1.0, v103
	v_rcp_f32_e32 v102, v102
	v_rcp_f32_e32 v103, v98
	v_mul_f32_e32 v98, v132, v99
	v_lshlrev_b32_e32 v106, 16, v165
	v_and_b32_e32 v107, 0xffff0000, v165
	v_exp_f32_e32 v105, v98
	v_lshlrev_b32_e32 v98, 16, v161
	v_and_b32_e32 v99, 0xffff0000, v161
	v_pk_fma_f32 v[98:99], v[102:103], v[106:107], v[98:99]
	v_fmamk_f32 v103, v228, 0x3a800000, v221
	v_mul_f32_e32 v106, 0x4b800000, v103
	v_cmp_gt_f32_e32 vcc, s60, v103
	v_add_f32_e32 v102, 1.0, v105
	v_rcp_f32_e32 v105, v102
	v_cndmask_b32_e32 v103, v103, v106, vcc
	v_rsq_f32_e32 v108, v103
	v_lshlrev_b32_e32 v102, 16, v167
	v_and_b32_e32 v103, 0xffff0000, v167
	v_lshlrev_b32_e32 v106, 16, v163
	v_mul_f32_e32 v109, 0x45800000, v108
	v_cndmask_b32_e32 v108, v108, v109, vcc
	v_mul_f32_e32 v108, 0xbfb8aa3b, v108
	v_mul_f32_e32 v88, v108, v88
	v_mul_f32_e32 v93, v108, v93
	v_exp_f32_e32 v88, v88
	v_mul_f32_e32 v92, v108, v92
	v_exp_f32_e32 v93, v93
	v_exp_f32_e32 v92, v92
	v_and_b32_e32 v107, 0xffff0000, v163
	v_add_f32_e32 v88, 1.0, v88
	v_pk_fma_f32 v[102:103], v[104:105], v[102:103], v[106:107]
	global_store_dwordx4 v[112:113], v[96:99], off offset:512 nt
	global_store_dwordx4 v[112:113], v[100:103], off offset:528 nt
	v_add_f32_e32 v92, 1.0, v92
	v_rcp_f32_e32 v96, v88
	v_add_f32_e32 v88, 1.0, v93
	v_rcp_f32_e32 v93, v88
	v_mul_f32_e32 v88, v108, v89
	v_rcp_f32_e32 v92, v92
	v_exp_f32_e32 v97, v88
	v_mul_f32_e32 v90, v108, v90
	v_lshlrev_b32_e32 v98, 16, v156
	v_and_b32_e32 v99, 0xffff0000, v156
	v_lshlrev_b32_e32 v88, 16, v152
	v_and_b32_e32 v89, 0xffff0000, v152
	v_mul_f32_e32 v95, v108, v95
	v_pk_fma_f32 v[88:89], v[92:93], v[98:99], v[88:89]
	v_add_f32_e32 v92, 1.0, v97
	v_exp_f32_e32 v90, v90
	v_rcp_f32_e32 v97, v92
	v_mul_f32_e32 v94, v108, v94
	v_exp_f32_e32 v95, v95
	v_exp_f32_e32 v94, v94
	v_lshlrev_b32_e32 v92, 16, v158
	v_and_b32_e32 v93, 0xffff0000, v158
	v_lshlrev_b32_e32 v98, 16, v154
	v_and_b32_e32 v99, 0xffff0000, v154
	v_add_f32_e32 v90, 1.0, v90
	v_pk_fma_f32 v[92:93], v[96:97], v[92:93], v[98:99]
	v_rcp_f32_e32 v96, v90
	v_add_f32_e32 v90, 1.0, v95
	v_rcp_f32_e32 v95, v90
	v_mul_f32_e32 v90, v108, v91
	v_add_f32_e32 v94, 1.0, v94
	v_rcp_f32_e32 v94, v94
	v_exp_f32_e32 v97, v90
	v_lshlrev_b32_e32 v98, 16, v157
	v_and_b32_e32 v99, 0xffff0000, v157
	v_lshlrev_b32_e32 v90, 16, v153
	v_and_b32_e32 v91, 0xffff0000, v153
	v_mul_f32_e32 v80, v108, v80
	v_pk_fma_f32 v[90:91], v[94:95], v[98:99], v[90:91]
	v_add_f32_e32 v94, 1.0, v97
	v_mul_f32_e32 v85, v108, v85
	v_rcp_f32_e32 v97, v94
	v_exp_f32_e32 v80, v80
	v_mul_f32_e32 v84, v108, v84
	v_exp_f32_e32 v85, v85
	v_lshlrev_b32_e32 v94, 16, v159
	v_and_b32_e32 v95, 0xffff0000, v159
	v_lshlrev_b32_e32 v98, 16, v155
	v_and_b32_e32 v99, 0xffff0000, v155
	v_exp_f32_e32 v84, v84
	v_pk_fma_f32 v[94:95], v[96:97], v[94:95], v[98:99]
	v_lshl_add_u64 v[96:97], v[188:189], 2, s[70:71]
	v_add_f32_e32 v80, 1.0, v80
	global_store_dwordx4 v[96:97], v[88:91], off nt
	global_store_dwordx4 v[96:97], v[92:95], off offset:16 nt
	v_add_f32_e32 v84, 1.0, v84
	v_rcp_f32_e32 v88, v80
	v_add_f32_e32 v80, 1.0, v85
	v_rcp_f32_e32 v85, v80
	v_mul_f32_e32 v80, v108, v81
	v_rcp_f32_e32 v84, v84
	v_exp_f32_e32 v89, v80
	v_mul_f32_e32 v82, v108, v82
	s_waitcnt vmcnt(12)
	v_lshlrev_b32_e32 v90, 16, v148
	v_and_b32_e32 v91, 0xffff0000, v148
	v_lshlrev_b32_e32 v80, 16, v144
	v_and_b32_e32 v81, 0xffff0000, v144
	v_mul_f32_e32 v86, v108, v86
	v_mul_f32_e32 v87, v108, v87
	v_pk_fma_f32 v[80:81], v[84:85], v[90:91], v[80:81]
	v_add_f32_e32 v84, 1.0, v89
	v_exp_f32_e32 v82, v82
	v_rcp_f32_e32 v89, v84
	v_exp_f32_e32 v86, v86
	v_exp_f32_e32 v87, v87
	v_lshlrev_b32_e32 v84, 16, v150
	v_and_b32_e32 v85, 0xffff0000, v150
	v_lshlrev_b32_e32 v90, 16, v146
	v_and_b32_e32 v91, 0xffff0000, v146
	v_add_f32_e32 v82, 1.0, v82
	v_pk_fma_f32 v[84:85], v[88:89], v[84:85], v[90:91]
	v_add_f32_e32 v86, 1.0, v86
	v_rcp_f32_e32 v88, v82
	v_add_f32_e32 v82, 1.0, v87
	v_rcp_f32_e32 v86, v86
	v_rcp_f32_e32 v87, v82
	v_mul_f32_e32 v82, v108, v83
	v_lshlrev_b32_e32 v90, 16, v149
	v_and_b32_e32 v91, 0xffff0000, v149
	v_exp_f32_e32 v89, v82
	v_lshlrev_b32_e32 v82, 16, v145
	v_and_b32_e32 v83, 0xffff0000, v145
	v_pk_fma_f32 v[82:83], v[86:87], v[90:91], v[82:83]
	v_fmamk_f32 v87, v227, 0x3a800000, v221
	v_mul_f32_e32 v90, 0x4b800000, v87
	v_cmp_gt_f32_e32 vcc, s60, v87
	v_add_f32_e32 v86, 1.0, v89
	v_rcp_f32_e32 v89, v86
	v_cndmask_b32_e32 v87, v87, v90, vcc
	v_rsq_f32_e32 v92, v87
	v_lshlrev_b32_e32 v86, 16, v151
	v_and_b32_e32 v87, 0xffff0000, v151
	v_lshlrev_b32_e32 v90, 16, v147
	v_mul_f32_e32 v93, 0x45800000, v92
	v_cndmask_b32_e32 v92, v92, v93, vcc
	v_mul_f32_e32 v92, 0xbfb8aa3b, v92
	v_mul_f32_e32 v72, v92, v72
	v_mul_f32_e32 v77, v92, v77
	v_exp_f32_e32 v72, v72
	v_mul_f32_e32 v76, v92, v76
	v_exp_f32_e32 v77, v77
	v_exp_f32_e32 v76, v76
	v_and_b32_e32 v91, 0xffff0000, v147
	v_add_f32_e32 v72, 1.0, v72
	v_pk_fma_f32 v[86:87], v[88:89], v[86:87], v[90:91]
	global_store_dwordx4 v[96:97], v[80:83], off offset:512 nt
	global_store_dwordx4 v[96:97], v[84:87], off offset:528 nt
	v_add_f32_e32 v76, 1.0, v76
	v_rcp_f32_e32 v80, v72
	v_add_f32_e32 v72, 1.0, v77
	v_rcp_f32_e32 v77, v72
	v_mul_f32_e32 v72, v92, v73
	v_rcp_f32_e32 v76, v76
	v_exp_f32_e32 v81, v72
	v_mul_f32_e32 v74, v92, v74
	v_lshlrev_b32_e32 v82, 16, v140
	v_and_b32_e32 v83, 0xffff0000, v140
	v_lshlrev_b32_e32 v72, 16, v136
	v_and_b32_e32 v73, 0xffff0000, v136
	v_mul_f32_e32 v79, v92, v79
	v_pk_fma_f32 v[72:73], v[76:77], v[82:83], v[72:73]
	v_add_f32_e32 v76, 1.0, v81
	v_exp_f32_e32 v74, v74
	v_rcp_f32_e32 v81, v76
	v_mul_f32_e32 v78, v92, v78
	v_exp_f32_e32 v79, v79
	v_exp_f32_e32 v78, v78
	v_lshlrev_b32_e32 v76, 16, v142
	v_and_b32_e32 v77, 0xffff0000, v142
	v_lshlrev_b32_e32 v82, 16, v138
	v_and_b32_e32 v83, 0xffff0000, v138
	v_add_f32_e32 v74, 1.0, v74
	v_pk_fma_f32 v[76:77], v[80:81], v[76:77], v[82:83]
	v_rcp_f32_e32 v80, v74
	v_add_f32_e32 v74, 1.0, v79
	v_rcp_f32_e32 v79, v74
	v_mul_f32_e32 v74, v92, v75
	v_add_f32_e32 v78, 1.0, v78
	v_rcp_f32_e32 v78, v78
	v_exp_f32_e32 v81, v74
	v_lshlrev_b32_e32 v82, 16, v141
	v_and_b32_e32 v83, 0xffff0000, v141
	v_lshlrev_b32_e32 v74, 16, v137
	v_and_b32_e32 v75, 0xffff0000, v137
	v_mul_f32_e32 v64, v92, v64
	v_pk_fma_f32 v[74:75], v[78:79], v[82:83], v[74:75]
	v_add_f32_e32 v78, 1.0, v81
	v_mul_f32_e32 v69, v92, v69
	v_rcp_f32_e32 v81, v78
	v_exp_f32_e32 v64, v64
	v_mul_f32_e32 v68, v92, v68
	v_exp_f32_e32 v69, v69
	v_lshlrev_b32_e32 v78, 16, v143
	v_and_b32_e32 v79, 0xffff0000, v143
	v_lshlrev_b32_e32 v82, 16, v139
	v_and_b32_e32 v83, 0xffff0000, v139
	v_exp_f32_e32 v68, v68
	v_pk_fma_f32 v[78:79], v[80:81], v[78:79], v[82:83]
	v_lshl_add_u64 v[80:81], v[186:187], 2, s[70:71]
	v_add_f32_e32 v64, 1.0, v64
	global_store_dwordx4 v[80:81], v[72:75], off nt
	global_store_dwordx4 v[80:81], v[76:79], off offset:16 nt
	v_add_f32_e32 v68, 1.0, v68
	v_rcp_f32_e32 v72, v64
	v_add_f32_e32 v64, 1.0, v69
	v_rcp_f32_e32 v69, v64
	v_mul_f32_e32 v64, v92, v65
	v_rcp_f32_e32 v68, v68
	v_exp_f32_e32 v73, v64
	v_mul_f32_e32 v66, v92, v66
	s_waitcnt vmcnt(14)
	v_lshlrev_b32_e32 v74, 16, v128
	v_and_b32_e32 v75, 0xffff0000, v128
	v_lshlrev_b32_e32 v64, 16, v124
	v_and_b32_e32 v65, 0xffff0000, v124
	v_mul_f32_e32 v71, v92, v71
	v_pk_fma_f32 v[64:65], v[68:69], v[74:75], v[64:65]
	v_add_f32_e32 v68, 1.0, v73
	v_exp_f32_e32 v66, v66
	v_rcp_f32_e32 v73, v68
	v_mul_f32_e32 v70, v92, v70
	v_exp_f32_e32 v71, v71
	v_exp_f32_e32 v70, v70
	v_lshlrev_b32_e32 v68, 16, v130
	v_and_b32_e32 v69, 0xffff0000, v130
	v_lshlrev_b32_e32 v74, 16, v126
	v_and_b32_e32 v75, 0xffff0000, v126
	v_add_f32_e32 v66, 1.0, v66
	v_pk_fma_f32 v[68:69], v[72:73], v[68:69], v[74:75]
	v_rcp_f32_e32 v72, v66
	v_add_f32_e32 v66, 1.0, v71
	v_rcp_f32_e32 v71, v66
	v_mul_f32_e32 v66, v92, v67
	v_add_f32_e32 v70, 1.0, v70
	v_rcp_f32_e32 v70, v70
	v_exp_f32_e32 v73, v66
	v_lshlrev_b32_e32 v74, 16, v129
	v_and_b32_e32 v75, 0xffff0000, v129
	v_lshlrev_b32_e32 v66, 16, v125
	v_and_b32_e32 v67, 0xffff0000, v125
	v_pk_fma_f32 v[66:67], v[70:71], v[74:75], v[66:67]
	v_add_f32_e32 v70, 1.0, v73
	v_rcp_f32_e32 v73, v70
	v_lshlrev_b32_e32 v70, 16, v131
	v_and_b32_e32 v71, 0xffff0000, v131
	v_lshlrev_b32_e32 v74, 16, v127
	v_and_b32_e32 v75, 0xffff0000, v127
	v_lshl_add_u64 v[134:135], v[184:185], 0, s[10:11]
	v_pk_fma_f32 v[70:71], v[72:73], v[70:71], v[74:75]
	global_store_dwordx4 v[80:81], v[64:67], off offset:512 nt
	global_store_dwordx4 v[80:81], v[68:71], off offset:528 nt
	v_lshl_add_u64 v[124:125], v[184:185], 0, s[16:17]
	v_lshlrev_b64 v[64:65], 1, v[134:135]
	v_lshl_add_u64 v[66:67], s[14:15], 0, v[64:65]
	global_load_dwordx4 v[126:129], v[66:67], off
	v_lshl_add_u64 v[66:67], s[12:13], 0, v[64:65]
	global_load_dwordx4 v[130:133], v[66:67], off
	v_or_b32_e32 v64, 0x100, v64
	v_lshl_add_u64 v[66:67], s[12:13], 0, v[64:65]
	v_lshl_add_u64 v[64:65], s[14:15], 0, v[64:65]
	global_load_dwordx4 v[112:115], v[66:67], off
	global_load_dwordx4 v[116:119], v[64:65], off
	v_lshlrev_b64 v[64:65], 1, v[124:125]
	v_lshl_add_u64 v[66:67], s[12:13], 0, v[64:65]
	v_lshl_add_u64 v[68:69], s[14:15], 0, v[64:65]
	global_load_dwordx4 v[104:107], v[66:67], off
	global_load_dwordx4 v[108:111], v[68:69], off
	v_or_b32_e32 v64, 0x100, v64
	v_fmamk_f32 v70, v226, 0x3a800000, v221
	v_lshl_add_u64 v[66:67], s[12:13], 0, v[64:65]
	v_lshl_add_u64 v[64:65], s[14:15], 0, v[64:65]
	v_lshl_add_u64 v[122:123], v[184:185], 0, s[18:19]
	v_mul_f32_e32 v71, 0x4b800000, v70
	v_cmp_gt_f32_e32 vcc, s60, v70
	global_load_dwordx4 v[96:99], v[66:67], off
	global_load_dwordx4 v[100:103], v[64:65], off
	v_lshlrev_b64 v[64:65], 1, v[122:123]
	v_cndmask_b32_e32 v70, v70, v71, vcc
	v_lshl_add_u64 v[66:67], s[12:13], 0, v[64:65]
	v_lshl_add_u64 v[68:69], s[14:15], 0, v[64:65]
	v_or_b32_e32 v64, 0x100, v64
	v_rsq_f32_e32 v70, v70
	global_load_dwordx4 v[88:91], v[66:67], off
	global_load_dwordx4 v[92:95], v[68:69], off
	v_lshl_add_u64 v[66:67], s[12:13], 0, v[64:65]
	v_lshl_add_u64 v[64:65], s[14:15], 0, v[64:65]
	v_lshl_add_u64 v[120:121], v[184:185], 0, s[20:21]
	global_load_dwordx4 v[80:83], v[66:67], off
	global_load_dwordx4 v[84:87], v[64:65], off
	v_lshlrev_b64 v[64:65], 1, v[120:121]
	v_lshl_add_u64 v[66:67], s[12:13], 0, v[64:65]
	v_lshl_add_u64 v[68:69], s[14:15], 0, v[64:65]
	global_load_dwordx4 v[72:75], v[66:67], off
	global_load_dwordx4 v[76:79], v[68:69], off
	v_mul_f32_e32 v68, 0x45800000, v70
	v_cndmask_b32_e32 v140, v70, v68, vcc
	v_mul_f32_e32 v140, 0xbfb8aa3b, v140
	v_mul_f32_e32 v56, v140, v56
	v_mul_f32_e32 v61, v140, v61
	v_exp_f32_e32 v56, v56
	v_mul_f32_e32 v60, v140, v60
	v_exp_f32_e32 v61, v61
	v_exp_f32_e32 v60, v60
	v_add_f32_e32 v56, 1.0, v56
	v_rcp_f32_e32 v136, v56
	v_add_f32_e32 v56, 1.0, v61
	v_rcp_f32_e32 v61, v56
	v_mul_f32_e32 v56, v140, v57
	v_add_f32_e32 v60, 1.0, v60
	v_mul_f32_e32 v58, v140, v58
	v_rcp_f32_e32 v60, v60
	v_mul_f32_e32 v63, v140, v63
	v_exp_f32_e32 v58, v58
	v_mul_f32_e32 v62, v140, v62
	v_exp_f32_e32 v63, v63
	v_exp_f32_e32 v62, v62
	v_add_f32_e32 v58, 1.0, v58
	v_mul_f32_e32 v48, v140, v48
	v_add_f32_e32 v62, 1.0, v62
	v_rcp_f32_e32 v62, v62
	v_mul_f32_e32 v53, v140, v53
	v_exp_f32_e32 v48, v48
	v_mul_f32_e32 v52, v140, v52
	v_exp_f32_e32 v53, v53
	v_or_b32_e32 v64, 0x100, v64
	v_exp_f32_e32 v52, v52
	v_lshl_add_u64 v[66:67], s[12:13], 0, v[64:65]
	v_lshl_add_u64 v[68:69], s[14:15], 0, v[64:65]
	v_add_f32_e32 v48, 1.0, v48
	global_load_dwordx4 v[64:67], v[66:67], off
	s_nop 0
	global_load_dwordx4 v[68:71], v[68:69], off
	v_add_f32_e32 v52, 1.0, v52
	s_waitcnt vmcnt(15)
	v_lshlrev_b32_e32 v138, 16, v126
	v_and_b32_e32 v139, 0xffff0000, v126
	v_exp_f32_e32 v126, v56
	s_waitcnt vmcnt(14)
	v_lshlrev_b32_e32 v56, 16, v130
	v_and_b32_e32 v57, 0xffff0000, v130
	v_pk_fma_f32 v[56:57], v[60:61], v[138:139], v[56:57]
	v_add_f32_e32 v60, 1.0, v126
	v_rcp_f32_e32 v137, v60
	v_rcp_f32_e32 v126, v58
	v_add_f32_e32 v58, 1.0, v63
	v_rcp_f32_e32 v63, v58
	v_mul_f32_e32 v58, v140, v59
	v_lshlrev_b32_e32 v60, 16, v128
	v_and_b32_e32 v61, 0xffff0000, v128
	v_lshlrev_b32_e32 v138, 16, v132
	v_and_b32_e32 v139, 0xffff0000, v132
	v_pk_fma_f32 v[60:61], v[136:137], v[60:61], v[138:139]
	v_lshlrev_b32_e32 v136, 16, v127
	v_and_b32_e32 v137, 0xffff0000, v127
	v_exp_f32_e32 v127, v58
	v_lshlrev_b32_e32 v58, 16, v131
	v_and_b32_e32 v59, 0xffff0000, v131
	v_pk_fma_f32 v[58:59], v[62:63], v[136:137], v[58:59]
	v_add_f32_e32 v62, 1.0, v127
	v_rcp_f32_e32 v127, v62
	v_lshlrev_b32_e32 v62, 16, v129
	v_and_b32_e32 v63, 0xffff0000, v129
	v_lshlrev_b32_e32 v128, 16, v133
	v_and_b32_e32 v129, 0xffff0000, v133
	v_pk_fma_f32 v[62:63], v[126:127], v[62:63], v[128:129]
	v_lshl_add_u64 v[126:127], v[134:135], 2, s[70:71]
	global_store_dwordx4 v[126:127], v[56:59], off nt
	global_store_dwordx4 v[126:127], v[60:63], off offset:16 nt
	v_rcp_f32_e32 v52, v52
	v_rcp_f32_e32 v56, v48
	v_add_f32_e32 v48, 1.0, v53
	v_rcp_f32_e32 v53, v48
	v_mul_f32_e32 v48, v140, v49
	v_exp_f32_e32 v57, v48
	v_mul_f32_e32 v50, v140, v50
	s_waitcnt vmcnt(14)
	v_lshlrev_b32_e32 v58, 16, v116
	v_and_b32_e32 v59, 0xffff0000, v116
	v_lshlrev_b32_e32 v48, 16, v112
	v_and_b32_e32 v49, 0xffff0000, v112
	v_mul_f32_e32 v54, v140, v54
	v_mul_f32_e32 v55, v140, v55
	v_pk_fma_f32 v[48:49], v[52:53], v[58:59], v[48:49]
	v_add_f32_e32 v52, 1.0, v57
	v_exp_f32_e32 v50, v50
	v_rcp_f32_e32 v57, v52
	v_exp_f32_e32 v54, v54
	v_exp_f32_e32 v55, v55
	v_lshlrev_b32_e32 v52, 16, v118
	v_and_b32_e32 v53, 0xffff0000, v118
	v_lshlrev_b32_e32 v58, 16, v114
	v_and_b32_e32 v59, 0xffff0000, v114
	v_add_f32_e32 v50, 1.0, v50
	v_pk_fma_f32 v[52:53], v[56:57], v[52:53], v[58:59]
	v_add_f32_e32 v54, 1.0, v54
	v_rcp_f32_e32 v56, v50
	v_add_f32_e32 v50, 1.0, v55
	v_rcp_f32_e32 v54, v54
	v_rcp_f32_e32 v55, v50
	v_mul_f32_e32 v50, v140, v51
	v_lshlrev_b32_e32 v58, 16, v117
	v_and_b32_e32 v59, 0xffff0000, v117
	v_exp_f32_e32 v57, v50
	v_lshlrev_b32_e32 v50, 16, v113
	v_and_b32_e32 v51, 0xffff0000, v113
	v_pk_fma_f32 v[50:51], v[54:55], v[58:59], v[50:51]
	v_fmamk_f32 v55, v225, 0x3a800000, v221
	v_mul_f32_e32 v58, 0x4b800000, v55
	v_cmp_gt_f32_e32 vcc, s60, v55
	v_add_f32_e32 v54, 1.0, v57
	v_rcp_f32_e32 v57, v54
	v_cndmask_b32_e32 v55, v55, v58, vcc
	v_rsq_f32_e32 v60, v55
	v_lshlrev_b32_e32 v54, 16, v119
	v_and_b32_e32 v55, 0xffff0000, v119
	v_lshlrev_b32_e32 v58, 16, v115
	v_mul_f32_e32 v61, 0x45800000, v60
	v_cndmask_b32_e32 v60, v60, v61, vcc
	v_mul_f32_e32 v60, 0xbfb8aa3b, v60
	v_mul_f32_e32 v40, v60, v40
	v_mul_f32_e32 v45, v60, v45
	v_exp_f32_e32 v40, v40
	v_mul_f32_e32 v44, v60, v44
	v_exp_f32_e32 v45, v45
	v_exp_f32_e32 v44, v44
	v_and_b32_e32 v59, 0xffff0000, v115
	v_add_f32_e32 v40, 1.0, v40
	v_pk_fma_f32 v[54:55], v[56:57], v[54:55], v[58:59]
	global_store_dwordx4 v[126:127], v[48:51], off offset:512 nt
	global_store_dwordx4 v[126:127], v[52:55], off offset:528 nt
	v_add_f32_e32 v44, 1.0, v44
	v_rcp_f32_e32 v48, v40
	v_add_f32_e32 v40, 1.0, v45
	v_rcp_f32_e32 v45, v40
	v_mul_f32_e32 v40, v60, v41
	v_rcp_f32_e32 v44, v44
	v_exp_f32_e32 v49, v40
	v_mul_f32_e32 v42, v60, v42
	s_waitcnt vmcnt(14)
	v_lshlrev_b32_e32 v50, 16, v108
	v_and_b32_e32 v51, 0xffff0000, v108
	v_lshlrev_b32_e32 v40, 16, v104
	v_and_b32_e32 v41, 0xffff0000, v104
	v_mul_f32_e32 v47, v60, v47
	v_pk_fma_f32 v[40:41], v[44:45], v[50:51], v[40:41]
	v_add_f32_e32 v44, 1.0, v49
	v_exp_f32_e32 v42, v42
	v_rcp_f32_e32 v49, v44
	v_mul_f32_e32 v46, v60, v46
	v_exp_f32_e32 v47, v47
	v_exp_f32_e32 v46, v46
	v_lshlrev_b32_e32 v44, 16, v110
	v_and_b32_e32 v45, 0xffff0000, v110
	v_lshlrev_b32_e32 v50, 16, v106
	v_and_b32_e32 v51, 0xffff0000, v106
	v_add_f32_e32 v42, 1.0, v42
	v_pk_fma_f32 v[44:45], v[48:49], v[44:45], v[50:51]
	v_rcp_f32_e32 v48, v42
	v_add_f32_e32 v42, 1.0, v47
	v_rcp_f32_e32 v47, v42
	v_mul_f32_e32 v42, v60, v43
	v_add_f32_e32 v46, 1.0, v46
	v_rcp_f32_e32 v46, v46
	v_exp_f32_e32 v49, v42
	v_lshlrev_b32_e32 v50, 16, v109
	v_and_b32_e32 v51, 0xffff0000, v109
	v_lshlrev_b32_e32 v42, 16, v105
	v_and_b32_e32 v43, 0xffff0000, v105
	v_mul_f32_e32 v32, v60, v32
	v_pk_fma_f32 v[42:43], v[46:47], v[50:51], v[42:43]
	v_add_f32_e32 v46, 1.0, v49
	v_mul_f32_e32 v37, v60, v37
	v_rcp_f32_e32 v49, v46
	v_exp_f32_e32 v32, v32
	v_mul_f32_e32 v36, v60, v36
	v_exp_f32_e32 v37, v37
	v_lshlrev_b32_e32 v46, 16, v111
	v_and_b32_e32 v47, 0xffff0000, v111
	v_lshlrev_b32_e32 v50, 16, v107
	v_and_b32_e32 v51, 0xffff0000, v107
	v_exp_f32_e32 v36, v36
	v_pk_fma_f32 v[46:47], v[48:49], v[46:47], v[50:51]
	v_lshl_add_u64 v[48:49], v[124:125], 2, s[70:71]
	v_add_f32_e32 v32, 1.0, v32
	global_store_dwordx4 v[48:49], v[40:43], off nt
	global_store_dwordx4 v[48:49], v[44:47], off offset:16 nt
	v_add_f32_e32 v36, 1.0, v36
	v_rcp_f32_e32 v40, v32
	v_add_f32_e32 v32, 1.0, v37
	v_rcp_f32_e32 v37, v32
	v_mul_f32_e32 v32, v60, v33
	v_rcp_f32_e32 v36, v36
	v_exp_f32_e32 v41, v32
	v_mul_f32_e32 v34, v60, v34
	s_waitcnt vmcnt(14)
	v_lshlrev_b32_e32 v42, 16, v100
	v_and_b32_e32 v43, 0xffff0000, v100
	v_lshlrev_b32_e32 v32, 16, v96
	v_and_b32_e32 v33, 0xffff0000, v96
	v_mul_f32_e32 v38, v60, v38
	v_mul_f32_e32 v39, v60, v39
	v_pk_fma_f32 v[32:33], v[36:37], v[42:43], v[32:33]
	v_add_f32_e32 v36, 1.0, v41
	v_exp_f32_e32 v34, v34
	v_rcp_f32_e32 v41, v36
	v_exp_f32_e32 v38, v38
	v_exp_f32_e32 v39, v39
	v_lshlrev_b32_e32 v36, 16, v102
	v_and_b32_e32 v37, 0xffff0000, v102
	v_lshlrev_b32_e32 v42, 16, v98
	v_and_b32_e32 v43, 0xffff0000, v98
	v_add_f32_e32 v34, 1.0, v34
	v_pk_fma_f32 v[36:37], v[40:41], v[36:37], v[42:43]
	v_add_f32_e32 v38, 1.0, v38
	v_rcp_f32_e32 v40, v34
	v_add_f32_e32 v34, 1.0, v39
	v_rcp_f32_e32 v38, v38
	v_rcp_f32_e32 v39, v34
	v_mul_f32_e32 v34, v60, v35
	v_lshlrev_b32_e32 v42, 16, v101
	v_and_b32_e32 v43, 0xffff0000, v101
	v_exp_f32_e32 v41, v34
	v_lshlrev_b32_e32 v34, 16, v97
	v_and_b32_e32 v35, 0xffff0000, v97
	v_pk_fma_f32 v[34:35], v[38:39], v[42:43], v[34:35]
	v_fmamk_f32 v39, v224, 0x3a800000, v221
	v_mul_f32_e32 v42, 0x4b800000, v39
	v_cmp_gt_f32_e32 vcc, s60, v39
	v_add_f32_e32 v38, 1.0, v41
	v_rcp_f32_e32 v41, v38
	v_cndmask_b32_e32 v39, v39, v42, vcc
	v_rsq_f32_e32 v44, v39
	v_lshlrev_b32_e32 v38, 16, v103
	v_and_b32_e32 v39, 0xffff0000, v103
	v_lshlrev_b32_e32 v42, 16, v99
	v_mul_f32_e32 v45, 0x45800000, v44
	v_cndmask_b32_e32 v44, v44, v45, vcc
	v_mul_f32_e32 v44, 0xbfb8aa3b, v44
	v_mul_f32_e32 v24, v44, v24
	v_mul_f32_e32 v29, v44, v29
	v_exp_f32_e32 v24, v24
	v_mul_f32_e32 v28, v44, v28
	v_exp_f32_e32 v29, v29
	v_exp_f32_e32 v28, v28
	v_and_b32_e32 v43, 0xffff0000, v99
	v_add_f32_e32 v24, 1.0, v24
	v_pk_fma_f32 v[38:39], v[40:41], v[38:39], v[42:43]
	global_store_dwordx4 v[48:49], v[32:35], off offset:512 nt
	global_store_dwordx4 v[48:49], v[36:39], off offset:528 nt
	v_add_f32_e32 v28, 1.0, v28
	v_rcp_f32_e32 v32, v24
	v_add_f32_e32 v24, 1.0, v29
	v_rcp_f32_e32 v29, v24
	v_mul_f32_e32 v24, v44, v25
	v_rcp_f32_e32 v28, v28
	v_exp_f32_e32 v33, v24
	v_mul_f32_e32 v26, v44, v26
	s_waitcnt vmcnt(14)
	v_lshlrev_b32_e32 v34, 16, v92
	v_and_b32_e32 v35, 0xffff0000, v92
	v_lshlrev_b32_e32 v24, 16, v88
	v_and_b32_e32 v25, 0xffff0000, v88
	v_mul_f32_e32 v31, v44, v31
	v_pk_fma_f32 v[24:25], v[28:29], v[34:35], v[24:25]
	v_add_f32_e32 v28, 1.0, v33
	v_exp_f32_e32 v26, v26
	v_rcp_f32_e32 v33, v28
	v_mul_f32_e32 v30, v44, v30
	v_exp_f32_e32 v31, v31
	v_exp_f32_e32 v30, v30
	v_lshlrev_b32_e32 v28, 16, v94
	v_and_b32_e32 v29, 0xffff0000, v94
	v_lshlrev_b32_e32 v34, 16, v90
	v_and_b32_e32 v35, 0xffff0000, v90
	v_add_f32_e32 v26, 1.0, v26
	v_pk_fma_f32 v[28:29], v[32:33], v[28:29], v[34:35]
	v_rcp_f32_e32 v32, v26
	v_add_f32_e32 v26, 1.0, v31
	v_rcp_f32_e32 v31, v26
	v_mul_f32_e32 v26, v44, v27
	v_add_f32_e32 v30, 1.0, v30
	v_rcp_f32_e32 v30, v30
	v_exp_f32_e32 v33, v26
	v_lshlrev_b32_e32 v34, 16, v93
	v_and_b32_e32 v35, 0xffff0000, v93
	v_lshlrev_b32_e32 v26, 16, v89
	v_and_b32_e32 v27, 0xffff0000, v89
	v_mul_f32_e32 v16, v44, v16
	v_pk_fma_f32 v[26:27], v[30:31], v[34:35], v[26:27]
	v_add_f32_e32 v30, 1.0, v33
	v_mul_f32_e32 v21, v44, v21
	v_rcp_f32_e32 v33, v30
	v_exp_f32_e32 v16, v16
	v_mul_f32_e32 v20, v44, v20
	v_exp_f32_e32 v21, v21
	v_lshlrev_b32_e32 v30, 16, v95
	v_and_b32_e32 v31, 0xffff0000, v95
	v_lshlrev_b32_e32 v34, 16, v91
	v_and_b32_e32 v35, 0xffff0000, v91
	v_exp_f32_e32 v20, v20
	v_pk_fma_f32 v[30:31], v[32:33], v[30:31], v[34:35]
	v_lshl_add_u64 v[32:33], v[122:123], 2, s[70:71]
	v_add_f32_e32 v16, 1.0, v16
	global_store_dwordx4 v[32:33], v[24:27], off nt
	global_store_dwordx4 v[32:33], v[28:31], off offset:16 nt
	v_add_f32_e32 v20, 1.0, v20
	v_rcp_f32_e32 v24, v16
	v_add_f32_e32 v16, 1.0, v21
	v_rcp_f32_e32 v21, v16
	v_mul_f32_e32 v16, v44, v17
	v_rcp_f32_e32 v20, v20
	v_exp_f32_e32 v25, v16
	v_mul_f32_e32 v18, v44, v18
	s_waitcnt vmcnt(14)
	v_lshlrev_b32_e32 v26, 16, v84
	v_and_b32_e32 v27, 0xffff0000, v84
	v_lshlrev_b32_e32 v16, 16, v80
	v_and_b32_e32 v17, 0xffff0000, v80
	v_mul_f32_e32 v22, v44, v22
	v_mul_f32_e32 v23, v44, v23
	v_pk_fma_f32 v[16:17], v[20:21], v[26:27], v[16:17]
	v_add_f32_e32 v20, 1.0, v25
	v_exp_f32_e32 v18, v18
	v_rcp_f32_e32 v25, v20
	v_exp_f32_e32 v22, v22
	v_exp_f32_e32 v23, v23
	v_lshlrev_b32_e32 v20, 16, v86
	v_and_b32_e32 v21, 0xffff0000, v86
	v_lshlrev_b32_e32 v26, 16, v82
	v_and_b32_e32 v27, 0xffff0000, v82
	v_add_f32_e32 v18, 1.0, v18
	v_pk_fma_f32 v[20:21], v[24:25], v[20:21], v[26:27]
	v_add_f32_e32 v22, 1.0, v22
	v_rcp_f32_e32 v24, v18
	v_add_f32_e32 v18, 1.0, v23
	v_rcp_f32_e32 v22, v22
	v_rcp_f32_e32 v23, v18
	v_mul_f32_e32 v18, v44, v19
	v_lshlrev_b32_e32 v26, 16, v85
	v_and_b32_e32 v27, 0xffff0000, v85
	v_exp_f32_e32 v25, v18
	v_lshlrev_b32_e32 v18, 16, v81
	v_and_b32_e32 v19, 0xffff0000, v81
	v_pk_fma_f32 v[18:19], v[22:23], v[26:27], v[18:19]
	v_fmamk_f32 v23, v223, 0x3a800000, v221
	v_mul_f32_e32 v26, 0x4b800000, v23
	v_cmp_gt_f32_e32 vcc, s60, v23
	v_add_f32_e32 v22, 1.0, v25
	v_rcp_f32_e32 v25, v22
	v_cndmask_b32_e32 v23, v23, v26, vcc
	v_rsq_f32_e32 v28, v23
	v_lshlrev_b32_e32 v22, 16, v87
	v_and_b32_e32 v23, 0xffff0000, v87
	v_lshlrev_b32_e32 v26, 16, v83
	v_mul_f32_e32 v29, 0x45800000, v28
	v_cndmask_b32_e32 v28, v28, v29, vcc
	v_mul_f32_e32 v28, 0xbfb8aa3b, v28
	v_mul_f32_e32 v8, v28, v8
	v_mul_f32_e32 v13, v28, v13
	v_exp_f32_e32 v8, v8
	v_mul_f32_e32 v12, v28, v12
	v_exp_f32_e32 v13, v13
	v_exp_f32_e32 v12, v12
	v_and_b32_e32 v27, 0xffff0000, v83
	v_add_f32_e32 v8, 1.0, v8
	v_pk_fma_f32 v[22:23], v[24:25], v[22:23], v[26:27]
	global_store_dwordx4 v[32:33], v[16:19], off offset:512 nt
	global_store_dwordx4 v[32:33], v[20:23], off offset:528 nt
	v_add_f32_e32 v12, 1.0, v12
	v_rcp_f32_e32 v16, v8
	v_add_f32_e32 v8, 1.0, v13
	v_rcp_f32_e32 v13, v8
	v_mul_f32_e32 v8, v28, v9
	v_rcp_f32_e32 v12, v12
	v_exp_f32_e32 v17, v8
	v_mul_f32_e32 v10, v28, v10
	s_waitcnt vmcnt(14)
	v_lshlrev_b32_e32 v18, 16, v76
	v_and_b32_e32 v19, 0xffff0000, v76
	v_lshlrev_b32_e32 v8, 16, v72
	v_and_b32_e32 v9, 0xffff0000, v72
	v_mul_f32_e32 v15, v28, v15
	v_pk_fma_f32 v[8:9], v[12:13], v[18:19], v[8:9]
	v_add_f32_e32 v12, 1.0, v17
	v_exp_f32_e32 v10, v10
	v_rcp_f32_e32 v17, v12
	v_mul_f32_e32 v14, v28, v14
	v_exp_f32_e32 v15, v15
	v_exp_f32_e32 v14, v14
	v_lshlrev_b32_e32 v12, 16, v78
	v_and_b32_e32 v13, 0xffff0000, v78
	v_lshlrev_b32_e32 v18, 16, v74
	v_and_b32_e32 v19, 0xffff0000, v74
	v_add_f32_e32 v10, 1.0, v10
	v_pk_fma_f32 v[12:13], v[16:17], v[12:13], v[18:19]
	v_rcp_f32_e32 v16, v10
	v_add_f32_e32 v10, 1.0, v15
	v_rcp_f32_e32 v15, v10
	v_mul_f32_e32 v10, v28, v11
	v_add_f32_e32 v14, 1.0, v14
	v_rcp_f32_e32 v14, v14
	v_exp_f32_e32 v17, v10
	v_lshlrev_b32_e32 v18, 16, v77
	v_and_b32_e32 v19, 0xffff0000, v77
	v_lshlrev_b32_e32 v10, 16, v73
	v_and_b32_e32 v11, 0xffff0000, v73
	v_mul_f32_e32 v0, v28, v0
	v_pk_fma_f32 v[10:11], v[14:15], v[18:19], v[10:11]
	v_add_f32_e32 v14, 1.0, v17
	v_mul_f32_e32 v5, v28, v5
	v_rcp_f32_e32 v17, v14
	v_exp_f32_e32 v0, v0
	v_mul_f32_e32 v4, v28, v4
	v_exp_f32_e32 v5, v5
	v_lshlrev_b32_e32 v14, 16, v79
	v_and_b32_e32 v15, 0xffff0000, v79
	v_lshlrev_b32_e32 v18, 16, v75
	v_and_b32_e32 v19, 0xffff0000, v75
	v_exp_f32_e32 v4, v4
	v_pk_fma_f32 v[14:15], v[16:17], v[14:15], v[18:19]
	v_lshl_add_u64 v[16:17], v[120:121], 2, s[70:71]
	v_add_f32_e32 v0, 1.0, v0
	global_store_dwordx4 v[16:17], v[8:11], off nt
	global_store_dwordx4 v[16:17], v[12:15], off offset:16 nt
	v_add_f32_e32 v4, 1.0, v4
	v_rcp_f32_e32 v8, v0
	v_add_f32_e32 v0, 1.0, v5
	v_rcp_f32_e32 v5, v0
	v_mul_f32_e32 v0, v28, v1
	v_rcp_f32_e32 v4, v4
	v_exp_f32_e32 v9, v0
	v_mul_f32_e32 v2, v28, v2
	s_waitcnt vmcnt(14)
	v_lshlrev_b32_e32 v10, 16, v68
	v_and_b32_e32 v11, 0xffff0000, v68
	v_lshlrev_b32_e32 v0, 16, v64
	v_and_b32_e32 v1, 0xffff0000, v64
	v_mul_f32_e32 v7, v28, v7
	v_pk_fma_f32 v[0:1], v[4:5], v[10:11], v[0:1]
	v_add_f32_e32 v4, 1.0, v9
	v_exp_f32_e32 v2, v2
	v_rcp_f32_e32 v9, v4
	v_mul_f32_e32 v6, v28, v6
	v_exp_f32_e32 v7, v7
	v_exp_f32_e32 v6, v6
	v_lshlrev_b32_e32 v4, 16, v70
	v_and_b32_e32 v5, 0xffff0000, v70
	v_lshlrev_b32_e32 v10, 16, v66
	v_and_b32_e32 v11, 0xffff0000, v66
	v_add_f32_e32 v2, 1.0, v2
	v_pk_fma_f32 v[4:5], v[8:9], v[4:5], v[10:11]
	v_rcp_f32_e32 v8, v2
	v_add_f32_e32 v2, 1.0, v7
	v_rcp_f32_e32 v7, v2
	v_mul_f32_e32 v2, v28, v3
	v_add_f32_e32 v6, 1.0, v6
	v_rcp_f32_e32 v6, v6
	v_exp_f32_e32 v9, v2
	v_lshlrev_b32_e32 v10, 16, v69
	v_and_b32_e32 v11, 0xffff0000, v69
	v_lshlrev_b32_e32 v2, 16, v65
	v_and_b32_e32 v3, 0xffff0000, v65
	v_pk_fma_f32 v[2:3], v[6:7], v[10:11], v[2:3]
	v_add_f32_e32 v6, 1.0, v9
	v_rcp_f32_e32 v9, v6
	v_lshlrev_b32_e32 v6, 16, v71
	v_and_b32_e32 v7, 0xffff0000, v71
	v_lshlrev_b32_e32 v10, 16, v67
	v_and_b32_e32 v11, 0xffff0000, v67
	v_pk_fma_f32 v[6:7], v[8:9], v[6:7], v[10:11]
	global_store_dwordx4 v[16:17], v[0:3], off offset:512 nt
	global_store_dwordx4 v[16:17], v[4:7], off offset:528 nt
	s_andn2_b64 vcc, exec, s[28:29]
	s_mov_b64 s[28:29], -1
	s_cbranch_vccnz .LBB0_1498
	s_andn2_b64 vcc, exec, s[0:1]
	s_cbranch_vccnz .LBB0_1497
	s_barrier
	s_branch .LBB0_1497
